# GEMM K-loop: in the 16-read sections the B1 fragment reads are issued last and waited (lgkmcnt 0) only before the second MFMA group; barrier wait relaxed to lgkmcnt(4)
# baseline (speedup 1.0000x reference)
; #define PG8_STAGE(bufoff, gbase, voff) do { _Pragma("unroll") for (int _i = 0; _i < 2; ++_i) \
;         __builtin_amdgcn_global_load_lds((const unsigned*)((const char*)(gbase) + (voff)[_i]), (PG8_LAS unsigned*)(lds + (bufoff) + ldsw + _i * 8192), 16, 0, 0); } while (0)
; #define PG8_LDA(dst, b, h) do { _Pragma("unroll") for (int m = 0; m < 4; ++m) _Pragma("unroll") for (int k = 0; k < 2; ++k) dst[m][k] = *(const PG8_LAS bf16x8*)(lds + PG8_SA(b, h) + aoff + m * 2048 + k * 1024); } while (0)
; #define PG8_LDB(dst, b, h) do { _Pragma("unroll") for (int n = 0; n < 2; ++n) _Pragma("unroll") for (int k = 0; k < 2; ++k) dst[n][k] = *(const PG8_LAS bf16x8*)(lds + PG8_SB(b, h) + boff + n * 2048 + k * 1024); } while (0)
; #define PG8_MMA(ai, bj, At, Bt) do { __builtin_amdgcn_s_setprio(1); _Pragma("unroll") for (int m = 0; m < 4; ++m) _Pragma("unroll") for (int n = 0; n < 2; ++n) _Pragma("unroll") for (int k = 0; k < 2; ++k) \
;         acc[ai][bj][m][n] = __builtin_amdgcn_mfma_f32_16x16x32_bf16(Bt[n][k], At[m][k], acc[ai][bj][m][n], 0, 0, 0); __builtin_amdgcn_s_setprio(0); } while (0)
; #define PG8_WAIT_V(n) asm volatile("s_waitcnt vmcnt(" #n ")" ::: "memory")
; #define PG8_WAIT_L(n) asm volatile("s_waitcnt lgkmcnt(" #n ")" ::: "memory")
; #define PG8_BAR __builtin_amdgcn_s_barrier()
; #define PG8_SCHED __builtin_amdgcn_sched_barrier(0)
; template <class Epi, class Sched>
; __device__ __forceinline__ void gemm_phase(PG8_LAS unsigned char* lds, const Gemm g, const Sched& S, const Epi& E) {
;     ...
;             PG8_LDB(B0, 0, 0); PG8_LDB(B1, 0, 1); PG8_SCHED; PG8_LDA(At, 0, 0); PG8_STAGE(PG8_SA(1, 1), a1 + hstepA, voffA);
;             PG8_WAIT_V(8); PG8_WAIT_L(0); PG8_BAR; PG8_MMA(0, 0, At, B0); PG8_MMA(0, 1, At, B1); PG8_BAR; PG8_SCHED;
;             PG8_LDA(At, 0, 1); PG8_STAGE(PG8_SB(0, 0), b2, voffB); PG8_STAGE(PG8_SB(0, 1), b2 + hstepB, voffB); PG8_STAGE(PG8_SA(0, 0), a2, voffA);
;             PG8_WAIT_V(8); PG8_WAIT_L(0); PG8_BAR; PG8_MMA(1, 0, At, B0); PG8_MMA(1, 1, At, B1); PG8_BAR; PG8_SCHED;
.LBB0_24:
	s_add_u32 s9, s28, 0xfff80080
	s_addc_u32 s10, s29, -1
	s_add_i32 s11, 0, 0x10000
	s_cmp_eq_u32 s8, 28
	s_cselect_b32 s43, s5, s10
	s_cselect_b32 s42, s13, s9
	v_add_u32_e32 v140, s11, v143
	s_cselect_b32 s39, s59, s7
	s_cselect_b32 s38, s61, s6
	s_add_i32 s9, 0, 0x14000
	ds_read_b128 v[146:149], v140
	ds_read_b128 v[150:153], v140 offset:1024
	ds_read_b128 v[154:157], v140 offset:2048
	ds_read_b128 v[158:161], v140 offset:3072
	ds_read_b128 v[186:189], v145
	ds_read_b128 v[190:193], v145 offset:1024
	ds_read_b128 v[194:197], v145 offset:2048
	ds_read_b128 v[198:201], v145 offset:3072
	ds_read_b128 v[202:205], v145 offset:4096
	ds_read_b128 v[216:219], v145 offset:5120
	ds_read_b128 v[220:223], v145 offset:6144
	ds_read_b128 v[224:227], v145 offset:7168
	v_add_u32_e32 v140, s9, v143
	ds_read_b128 v[170:173], v140
	ds_read_b128 v[174:177], v140 offset:1024
	ds_read_b128 v[178:181], v140 offset:2048
	ds_read_b128 v[182:185], v140 offset:3072
	v_lshl_add_u64 v[140:141], s[28:29], 0, v[136:137]
	s_add_i32 m0, s82, 0xc000
	global_load_lds_dwordx4 v[140:141], off
	v_lshl_add_u64 v[140:141], s[28:29], 0, v[138:139]
	s_add_i32 m0, s82, 0xe000
	s_nop 0
	global_load_lds_dwordx4 v[140:141], off
	s_waitcnt vmcnt(8)
	s_waitcnt lgkmcnt(4)
	s_barrier
	s_setprio 1
	s_waitcnt lgkmcnt(4)
	v_mfma_f32_16x16x32_bf16 v[118:121], v[146:149], v[186:189], v[118:121]
	v_mfma_f32_16x16x32_bf16 v[114:117], v[154:157], v[186:189], v[114:117]
	v_mfma_f32_16x16x32_bf16 v[110:113], v[146:149], v[194:197], v[110:113]
	v_mfma_f32_16x16x32_bf16 v[102:105], v[154:157], v[194:197], v[102:105]
	v_mfma_f32_16x16x32_bf16 v[86:89], v[146:149], v[202:205], v[86:89]
	v_mfma_f32_16x16x32_bf16 v[82:85], v[154:157], v[202:205], v[82:85]
	v_mfma_f32_16x16x32_bf16 v[78:81], v[146:149], v[220:223], v[78:81]
	v_mfma_f32_16x16x32_bf16 v[70:73], v[154:157], v[220:223], v[70:73]
	v_mfma_f32_16x16x32_bf16 v[118:121], v[150:153], v[190:193], v[118:121]
	v_mfma_f32_16x16x32_bf16 v[114:117], v[158:161], v[190:193], v[114:117]
	v_mfma_f32_16x16x32_bf16 v[110:113], v[150:153], v[198:201], v[110:113]
	v_mfma_f32_16x16x32_bf16 v[102:105], v[158:161], v[198:201], v[102:105]
	v_mfma_f32_16x16x32_bf16 v[86:89], v[150:153], v[216:219], v[86:89]
	v_mfma_f32_16x16x32_bf16 v[82:85], v[158:161], v[216:219], v[82:85]
	v_mfma_f32_16x16x32_bf16 v[78:81], v[150:153], v[224:227], v[78:81]
	v_mfma_f32_16x16x32_bf16 v[70:73], v[158:161], v[224:227], v[70:73]
	s_setprio 0
	s_setprio 1
	s_waitcnt lgkmcnt(0)
	v_mfma_f32_16x16x32_bf16 v[126:129], v[170:173], v[186:189], v[126:129]
	v_mfma_f32_16x16x32_bf16 v[122:125], v[178:181], v[186:189], v[122:125]
	v_mfma_f32_16x16x32_bf16 v[106:109], v[170:173], v[194:197], v[106:109]
	v_mfma_f32_16x16x32_bf16 v[98:101], v[178:181], v[194:197], v[98:101]
	v_mfma_f32_16x16x32_bf16 v[94:97], v[170:173], v[202:205], v[94:97]
	v_mfma_f32_16x16x32_bf16 v[90:93], v[178:181], v[202:205], v[90:93]
	v_mfma_f32_16x16x32_bf16 v[74:77], v[170:173], v[220:223], v[74:77]
	v_mfma_f32_16x16x32_bf16 v[66:69], v[178:181], v[220:223], v[66:69]
	v_mfma_f32_16x16x32_bf16 v[126:129], v[174:177], v[190:193], v[126:129]
	v_mfma_f32_16x16x32_bf16 v[122:125], v[182:185], v[190:193], v[122:125]
	v_mfma_f32_16x16x32_bf16 v[106:109], v[174:177], v[198:201], v[106:109]
	v_mfma_f32_16x16x32_bf16 v[98:101], v[182:185], v[198:201], v[98:101]
	v_mfma_f32_16x16x32_bf16 v[94:97], v[174:177], v[216:219], v[94:97]
	v_mfma_f32_16x16x32_bf16 v[90:93], v[182:185], v[216:219], v[90:93]
	v_mfma_f32_16x16x32_bf16 v[74:77], v[174:177], v[224:227], v[74:77]
	v_mfma_f32_16x16x32_bf16 v[66:69], v[182:185], v[224:227], v[66:69]
	s_setprio 0
	s_barrier
	s_add_i32 s10, s11, s80
	v_lshl_add_u64 v[140:141], s[38:39], 0, v[0:1]
	s_mov_b32 m0, s10
	ds_read_b128 v[186:189], v145 offset:16384
	ds_read_b128 v[190:193], v145 offset:17408
	ds_read_b128 v[194:197], v145 offset:18432
	ds_read_b128 v[198:201], v145 offset:19456
	ds_read_b128 v[202:205], v145 offset:20480
	ds_read_b128 v[216:219], v145 offset:21504
	ds_read_b128 v[220:223], v145 offset:22528
	ds_read_b128 v[224:227], v145 offset:23552
	global_load_lds_dwordx4 v[140:141], off
	s_add_i32 m0, s10, 0x2000
	s_add_u32 s10, s38, 0x80000
	v_lshl_add_u64 v[168:169], s[38:39], 0, v[130:131]
	s_addc_u32 s11, s39, 0
	s_add_i32 s9, s9, s80
	global_load_lds_dwordx4 v[168:169], off
	v_lshl_add_u64 v[228:229], s[10:11], 0, v[0:1]
	s_mov_b32 m0, s9
	v_lshl_add_u64 v[230:231], s[42:43], 0, v[132:133]
	global_load_lds_dwordx4 v[228:229], off
	v_lshl_add_u64 v[228:229], s[10:11], 0, v[130:131]
	s_add_i32 m0, s9, 0x2000
	s_nop 0
	global_load_lds_dwordx4 v[228:229], off
	v_lshl_add_u64 v[228:229], s[42:43], 0, v[134:135]
	s_mov_b32 m0, s82
	s_nop 0
	global_load_lds_dwordx4 v[228:229], off
	s_mov_b32 m0, s83
	s_nop 0
	global_load_lds_dwordx4 v[230:231], off
	s_waitcnt vmcnt(8)
	s_waitcnt lgkmcnt(0)
	s_barrier
; #define PG8_STAGE(bufoff, gbase, voff) do { _Pragma("unroll") for (int _i = 0; _i < 2; ++_i) \
;         __builtin_amdgcn_global_load_lds((const unsigned*)((const char*)(gbase) + (voff)[_i]), (PG8_LAS unsigned*)(lds + (bufoff) + ldsw + _i * 8192), 16, 0, 0); } while (0)
; #define PG8_LDA(dst, b, h) do { _Pragma("unroll") for (int m = 0; m < 4; ++m) _Pragma("unroll") for (int k = 0; k < 2; ++k) dst[m][k] = *(const PG8_LAS bf16x8*)(lds + PG8_SA(b, h) + aoff + m * 2048 + k * 1024); } while (0)
; #define PG8_LDB(dst, b, h) do { _Pragma("unroll") for (int n = 0; n < 2; ++n) _Pragma("unroll") for (int k = 0; k < 2; ++k) dst[n][k] = *(const PG8_LAS bf16x8*)(lds + PG8_SB(b, h) + boff + n * 2048 + k * 1024); } while (0)
; #define PG8_MMA(ai, bj, At, Bt) do { __builtin_amdgcn_s_setprio(1); _Pragma("unroll") for (int m = 0; m < 4; ++m) _Pragma("unroll") for (int n = 0; n < 2; ++n) _Pragma("unroll") for (int k = 0; k < 2; ++k) \
;         acc[ai][bj][m][n] = __builtin_amdgcn_mfma_f32_16x16x32_bf16(Bt[n][k], At[m][k], acc[ai][bj][m][n], 0, 0, 0); __builtin_amdgcn_s_setprio(0); } while (0)
; #define PG8_WAIT_V(n) asm volatile("s_waitcnt vmcnt(" #n ")" ::: "memory")
; #define PG8_WAIT_L(n) asm volatile("s_waitcnt lgkmcnt(" #n ")" ::: "memory")
; #define PG8_BAR __builtin_amdgcn_s_barrier()
; #define PG8_SCHED __builtin_amdgcn_sched_barrier(0)
; template <class Epi, class Sched>
; __device__ __forceinline__ void gemm_phase(PG8_LAS unsigned char* lds, const Gemm g, const Sched& S, const Epi& E) {
;     ...
;             PG8_WAIT_V(8); PG8_WAIT_L(0); PG8_BAR; PG8_MMA(1, 0, At, B0); PG8_MMA(1, 1, At, B1); PG8_BAR; PG8_SCHED;
;             PG8_LDB(B0, 1, 0); PG8_LDB(B1, 1, 1); PG8_SCHED; PG8_LDA(At, 1, 0); PG8_STAGE(PG8_SA(0, 1), a2 + hstepA, voffA);
;             PG8_WAIT_V(8); PG8_WAIT_L(0); PG8_BAR; PG8_MMA(0, 0, At, B0); PG8_MMA(0, 1, At, B1); PG8_BAR; PG8_SCHED;
	s_setprio 1
	s_waitcnt lgkmcnt(0)
	v_mfma_f32_16x16x32_bf16 v[54:57], v[146:149], v[186:189], v[54:57]
	v_mfma_f32_16x16x32_bf16 v[50:53], v[154:157], v[186:189], v[50:53]
	v_mfma_f32_16x16x32_bf16 v[46:49], v[146:149], v[194:197], v[46:49]
	v_mfma_f32_16x16x32_bf16 v[38:41], v[154:157], v[194:197], v[38:41]
	v_mfma_f32_16x16x32_bf16 v[22:25], v[146:149], v[202:205], v[22:25]
	v_mfma_f32_16x16x32_bf16 v[18:21], v[154:157], v[202:205], v[18:21]
	v_mfma_f32_16x16x32_bf16 v[14:17], v[146:149], v[220:223], v[14:17]
	v_mfma_f32_16x16x32_bf16 v[6:9], v[154:157], v[220:223], v[6:9]
	v_mfma_f32_16x16x32_bf16 v[54:57], v[150:153], v[190:193], v[54:57]
	v_mfma_f32_16x16x32_bf16 v[50:53], v[158:161], v[190:193], v[50:53]
	v_mfma_f32_16x16x32_bf16 v[46:49], v[150:153], v[198:201], v[46:49]
	v_mfma_f32_16x16x32_bf16 v[38:41], v[158:161], v[198:201], v[38:41]
	v_mfma_f32_16x16x32_bf16 v[22:25], v[150:153], v[216:219], v[22:25]
	v_mfma_f32_16x16x32_bf16 v[18:21], v[158:161], v[216:219], v[18:21]
	v_mfma_f32_16x16x32_bf16 v[14:17], v[150:153], v[224:227], v[14:17]
	v_mfma_f32_16x16x32_bf16 v[6:9], v[158:161], v[224:227], v[6:9]
	s_setprio 0
	s_setprio 1
	v_mfma_f32_16x16x32_bf16 v[62:65], v[170:173], v[186:189], v[62:65]
	v_mfma_f32_16x16x32_bf16 v[58:61], v[178:181], v[186:189], v[58:61]
	v_mfma_f32_16x16x32_bf16 v[42:45], v[170:173], v[194:197], v[42:45]
	v_mfma_f32_16x16x32_bf16 v[34:37], v[178:181], v[194:197], v[34:37]
	v_mfma_f32_16x16x32_bf16 v[30:33], v[170:173], v[202:205], v[30:33]
	v_mfma_f32_16x16x32_bf16 v[26:29], v[178:181], v[202:205], v[26:29]
	v_mfma_f32_16x16x32_bf16 v[10:13], v[170:173], v[220:223], v[10:13]
	v_mfma_f32_16x16x32_bf16 v[2:5], v[178:181], v[220:223], v[2:5]
	v_mfma_f32_16x16x32_bf16 v[62:65], v[174:177], v[190:193], v[62:65]
	v_mfma_f32_16x16x32_bf16 v[58:61], v[182:185], v[190:193], v[58:61]
	v_mfma_f32_16x16x32_bf16 v[42:45], v[174:177], v[198:201], v[42:45]
	v_mfma_f32_16x16x32_bf16 v[34:37], v[182:185], v[198:201], v[34:37]
	v_mfma_f32_16x16x32_bf16 v[30:33], v[174:177], v[216:219], v[30:33]
	v_mfma_f32_16x16x32_bf16 v[26:29], v[182:185], v[216:219], v[26:29]
	v_mfma_f32_16x16x32_bf16 v[10:13], v[174:177], v[224:227], v[10:13]
	v_mfma_f32_16x16x32_bf16 v[2:5], v[182:185], v[224:227], v[2:5]
	s_setprio 0
	s_barrier
	s_add_i32 s9, 0, 0x18000
	s_add_i32 s57, 0, 0x1c000
	v_add_u32_e32 v158, s9, v143
	v_add_u32_e32 v162, s57, v143
	ds_read_b128 v[146:149], v158
	ds_read_b128 v[150:153], v158 offset:1024
	ds_read_b128 v[154:157], v158 offset:2048
	ds_read_b128 v[158:161], v158 offset:3072
	ds_read_b128 v[186:189], v145 offset:32768
	ds_read_b128 v[190:193], v145 offset:33792
	ds_read_b128 v[194:197], v145 offset:34816
	ds_read_b128 v[198:201], v145 offset:35840
	ds_read_b128 v[202:205], v145 offset:36864
	ds_read_b128 v[216:219], v145 offset:37888
	ds_read_b128 v[220:223], v145 offset:38912
	ds_read_b128 v[224:227], v145 offset:39936
	ds_read_b128 v[170:173], v162
	ds_read_b128 v[174:177], v162 offset:1024
	ds_read_b128 v[178:181], v162 offset:2048
	ds_read_b128 v[182:185], v162 offset:3072
	s_add_u32 s10, s42, 0x80000
	s_addc_u32 s11, s43, 0
	s_mov_b32 m0, s84
	v_lshl_add_u64 v[232:233], s[10:11], 0, v[134:135]
	global_load_lds_dwordx4 v[232:233], off
	v_lshl_add_u64 v[232:233], s[10:11], 0, v[132:133]
	s_mov_b32 m0, s85
	s_nop 0
	global_load_lds_dwordx4 v[232:233], off
	s_waitcnt vmcnt(8)
	s_waitcnt lgkmcnt(4)
	s_barrier
	s_setprio 1
	s_waitcnt lgkmcnt(4)
	v_mfma_f32_16x16x32_bf16 v[118:121], v[146:149], v[186:189], v[118:121]
	v_mfma_f32_16x16x32_bf16 v[114:117], v[154:157], v[186:189], v[114:117]
	v_mfma_f32_16x16x32_bf16 v[110:113], v[146:149], v[194:197], v[110:113]
	v_mfma_f32_16x16x32_bf16 v[102:105], v[154:157], v[194:197], v[102:105]
	v_mfma_f32_16x16x32_bf16 v[86:89], v[146:149], v[202:205], v[86:89]
	v_mfma_f32_16x16x32_bf16 v[82:85], v[154:157], v[202:205], v[82:85]
	v_mfma_f32_16x16x32_bf16 v[78:81], v[146:149], v[220:223], v[78:81]
	v_mfma_f32_16x16x32_bf16 v[70:73], v[154:157], v[220:223], v[70:73]
	v_mfma_f32_16x16x32_bf16 v[118:121], v[150:153], v[190:193], v[118:121]
	v_mfma_f32_16x16x32_bf16 v[114:117], v[158:161], v[190:193], v[114:117]
	v_mfma_f32_16x16x32_bf16 v[110:113], v[150:153], v[198:201], v[110:113]
	v_mfma_f32_16x16x32_bf16 v[102:105], v[158:161], v[198:201], v[102:105]
	v_mfma_f32_16x16x32_bf16 v[86:89], v[150:153], v[216:219], v[86:89]
	v_mfma_f32_16x16x32_bf16 v[82:85], v[158:161], v[216:219], v[82:85]
	v_mfma_f32_16x16x32_bf16 v[78:81], v[150:153], v[224:227], v[78:81]
	v_mfma_f32_16x16x32_bf16 v[70:73], v[158:161], v[224:227], v[70:73]
	s_setprio 0
	s_setprio 1
	s_waitcnt lgkmcnt(0)
	v_mfma_f32_16x16x32_bf16 v[126:129], v[170:173], v[186:189], v[126:129]
	v_mfma_f32_16x16x32_bf16 v[122:125], v[178:181], v[186:189], v[122:125]
	v_mfma_f32_16x16x32_bf16 v[106:109], v[170:173], v[194:197], v[106:109]
	v_mfma_f32_16x16x32_bf16 v[98:101], v[178:181], v[194:197], v[98:101]
	v_mfma_f32_16x16x32_bf16 v[94:97], v[170:173], v[202:205], v[94:97]
	v_mfma_f32_16x16x32_bf16 v[90:93], v[178:181], v[202:205], v[90:93]
	v_mfma_f32_16x16x32_bf16 v[74:77], v[170:173], v[220:223], v[74:77]
	v_mfma_f32_16x16x32_bf16 v[66:69], v[178:181], v[220:223], v[66:69]
	v_mfma_f32_16x16x32_bf16 v[126:129], v[174:177], v[190:193], v[126:129]
	v_mfma_f32_16x16x32_bf16 v[122:125], v[182:185], v[190:193], v[122:125]
	v_mfma_f32_16x16x32_bf16 v[106:109], v[174:177], v[198:201], v[106:109]
	v_mfma_f32_16x16x32_bf16 v[98:101], v[182:185], v[198:201], v[98:101]
	v_mfma_f32_16x16x32_bf16 v[94:97], v[174:177], v[216:219], v[94:97]
	v_mfma_f32_16x16x32_bf16 v[90:93], v[182:185], v[216:219], v[90:93]
	v_mfma_f32_16x16x32_bf16 v[74:77], v[174:177], v[224:227], v[74:77]
	v_mfma_f32_16x16x32_bf16 v[66:69], v[182:185], v[224:227], v[66:69]
	s_setprio 0
	s_barrier
; #define PG8_STAGE(bufoff, gbase, voff) do { _Pragma("unroll") for (int _i = 0; _i < 2; ++_i) \
;         __builtin_amdgcn_global_load_lds((const unsigned*)((const char*)(gbase) + (voff)[_i]), (PG8_LAS unsigned*)(lds + (bufoff) + ldsw + _i * 8192), 16, 0, 0); } while (0)
; #define PG8_LDA(dst, b, h) do { _Pragma("unroll") for (int m = 0; m < 4; ++m) _Pragma("unroll") for (int k = 0; k < 2; ++k) dst[m][k] = *(const PG8_LAS bf16x8*)(lds + PG8_SA(b, h) + aoff + m * 2048 + k * 1024); } while (0)
; #define PG8_MMA(ai, bj, At, Bt) do { __builtin_amdgcn_s_setprio(1); _Pragma("unroll") for (int m = 0; m < 4; ++m) _Pragma("unroll") for (int n = 0; n < 2; ++n) _Pragma("unroll") for (int k = 0; k < 2; ++k) \
;         acc[ai][bj][m][n] = __builtin_amdgcn_mfma_f32_16x16x32_bf16(Bt[n][k], At[m][k], acc[ai][bj][m][n], 0, 0, 0); __builtin_amdgcn_s_setprio(0); } while (0)
; #define PG8_WAIT_V(n) asm volatile("s_waitcnt vmcnt(" #n ")" ::: "memory")
; #define PG8_WAIT_L(n) asm volatile("s_waitcnt lgkmcnt(" #n ")" ::: "memory")
; #define PG8_BAR __builtin_amdgcn_s_barrier()
; #define PG8_SCHED __builtin_amdgcn_sched_barrier(0)
; template <class Epi, class Sched>
; __device__ __forceinline__ void gemm_phase(PG8_LAS unsigned char* lds, const Gemm g, const Sched& S, const Epi& E) {
;     ...
;             PG8_LDA(At, 1, 1); PG8_STAGE(PG8_SB(1, 0), b3, voffB); PG8_STAGE(PG8_SB(1, 1), b3 + hstepB, voffB); PG8_STAGE(PG8_SA(1, 0), a3, voffA);
;             PG8_WAIT_V(8); PG8_WAIT_L(0); PG8_BAR; PG8_MMA(1, 0, At, B0); PG8_MMA(1, 1, At, B1); PG8_BAR; PG8_SCHED;
;         }
	s_add_i32 s9, s9, s80
	v_lshl_add_u64 v[140:141], v[140:141], 0, s[22:23]
	s_mov_b32 m0, s9
	ds_read_b128 v[186:189], v145 offset:49152
	ds_read_b128 v[190:193], v145 offset:50176
	ds_read_b128 v[194:197], v145 offset:51200
	ds_read_b128 v[198:201], v145 offset:52224
	ds_read_b128 v[202:205], v145 offset:53248
	ds_read_b128 v[216:219], v145 offset:54272
	ds_read_b128 v[220:223], v145 offset:55296
	ds_read_b128 v[224:227], v145 offset:56320
	global_load_lds_dwordx4 v[140:141], off
	s_add_i32 m0, s9, 0x2000
	s_add_u32 s10, s38, 0x80080
	v_lshl_add_u64 v[140:141], v[168:169], 0, s[22:23]
	s_addc_u32 s11, s39, 0
	s_add_i32 s9, s57, s80
	global_load_lds_dwordx4 v[140:141], off
	v_lshl_add_u64 v[140:141], s[10:11], 0, v[0:1]
	s_mov_b32 m0, s9
	s_nop 0
	global_load_lds_dwordx4 v[140:141], off
	v_lshl_add_u64 v[140:141], s[10:11], 0, v[130:131]
	s_add_i32 m0, s9, 0x2000
	s_nop 0
	global_load_lds_dwordx4 v[140:141], off
	v_lshl_add_u64 v[140:141], v[228:229], 0, s[22:23]
	s_mov_b32 m0, s20
	s_nop 0
	global_load_lds_dwordx4 v[140:141], off
	v_lshl_add_u64 v[140:141], v[230:231], 0, s[22:23]
	s_mov_b32 m0, s86
	s_nop 0
	global_load_lds_dwordx4 v[140:141], off
	s_waitcnt vmcnt(8)
	s_waitcnt lgkmcnt(0)
	s_barrier
	s_setprio 1
	s_waitcnt lgkmcnt(0)
	v_mfma_f32_16x16x32_bf16 v[54:57], v[146:149], v[186:189], v[54:57]
	v_mfma_f32_16x16x32_bf16 v[50:53], v[154:157], v[186:189], v[50:53]
	v_mfma_f32_16x16x32_bf16 v[46:49], v[146:149], v[194:197], v[46:49]
	v_mfma_f32_16x16x32_bf16 v[38:41], v[154:157], v[194:197], v[38:41]
	v_mfma_f32_16x16x32_bf16 v[22:25], v[146:149], v[202:205], v[22:25]
	v_mfma_f32_16x16x32_bf16 v[18:21], v[154:157], v[202:205], v[18:21]
	v_mfma_f32_16x16x32_bf16 v[14:17], v[146:149], v[220:223], v[14:17]
	v_mfma_f32_16x16x32_bf16 v[6:9], v[154:157], v[220:223], v[6:9]
	v_mfma_f32_16x16x32_bf16 v[54:57], v[150:153], v[190:193], v[54:57]
	v_mfma_f32_16x16x32_bf16 v[50:53], v[158:161], v[190:193], v[50:53]
	v_mfma_f32_16x16x32_bf16 v[46:49], v[150:153], v[198:201], v[46:49]
	v_mfma_f32_16x16x32_bf16 v[38:41], v[158:161], v[198:201], v[38:41]
	v_mfma_f32_16x16x32_bf16 v[22:25], v[150:153], v[216:219], v[22:25]
	v_mfma_f32_16x16x32_bf16 v[18:21], v[158:161], v[216:219], v[18:21]
	v_mfma_f32_16x16x32_bf16 v[14:17], v[150:153], v[224:227], v[14:17]
	v_mfma_f32_16x16x32_bf16 v[6:9], v[158:161], v[224:227], v[6:9]
	s_setprio 0
	s_setprio 1
	v_mfma_f32_16x16x32_bf16 v[62:65], v[170:173], v[186:189], v[62:65]
	v_mfma_f32_16x16x32_bf16 v[58:61], v[178:181], v[186:189], v[58:61]
	v_mfma_f32_16x16x32_bf16 v[42:45], v[170:173], v[194:197], v[42:45]
	v_mfma_f32_16x16x32_bf16 v[34:37], v[178:181], v[194:197], v[34:37]
	v_mfma_f32_16x16x32_bf16 v[30:33], v[170:173], v[202:205], v[30:33]
	v_mfma_f32_16x16x32_bf16 v[26:29], v[178:181], v[202:205], v[26:29]
	v_mfma_f32_16x16x32_bf16 v[10:13], v[170:173], v[220:223], v[10:13]
	v_mfma_f32_16x16x32_bf16 v[2:5], v[178:181], v[220:223], v[2:5]
	v_mfma_f32_16x16x32_bf16 v[62:65], v[174:177], v[190:193], v[62:65]
	v_mfma_f32_16x16x32_bf16 v[58:61], v[182:185], v[190:193], v[58:61]
	v_mfma_f32_16x16x32_bf16 v[42:45], v[174:177], v[198:201], v[42:45]
	v_mfma_f32_16x16x32_bf16 v[34:37], v[182:185], v[198:201], v[34:37]
	v_mfma_f32_16x16x32_bf16 v[30:33], v[174:177], v[216:219], v[30:33]
	v_mfma_f32_16x16x32_bf16 v[26:29], v[182:185], v[216:219], v[26:29]
	v_mfma_f32_16x16x32_bf16 v[10:13], v[174:177], v[224:227], v[10:13]
	v_mfma_f32_16x16x32_bf16 v[2:5], v[182:185], v[224:227], v[2:5]
	s_setprio 0
	s_barrier
	s_add_i32 s8, s8, 2
	s_add_u32 s28, s28, 0x100
	s_addc_u32 s29, s29, 0
	s_add_u32 s6, s6, 0x100
	s_addc_u32 s7, s7, 0
	s_cmp_gt_u32 s8, 29
	s_cbranch_scc0 .LBB0_24
	s_and_b64 vcc, exec, s[50:51]
	s_cbranch_vccz .LBB0_27
	s_barrier

; #define PG8_STAGE(bufoff, gbase, voff) do { _Pragma("unroll") for (int _i = 0; _i < 2; ++_i) \
;         __builtin_amdgcn_global_load_lds((const unsigned*)((const char*)(gbase) + (voff)[_i]), (PG8_LAS unsigned*)(lds + (bufoff) + ldsw + _i * 8192), 16, 0, 0); } while (0)
; #define PG8_LDA(dst, b, h) do { _Pragma("unroll") for (int m = 0; m < 4; ++m) _Pragma("unroll") for (int k = 0; k < 2; ++k) dst[m][k] = *(const PG8_LAS bf16x8*)(lds + PG8_SA(b, h) + aoff + m * 2048 + k * 1024); } while (0)
; #define PG8_LDB(dst, b, h) do { _Pragma("unroll") for (int n = 0; n < 2; ++n) _Pragma("unroll") for (int k = 0; k < 2; ++k) dst[n][k] = *(const PG8_LAS bf16x8*)(lds + PG8_SB(b, h) + boff + n * 2048 + k * 1024); } while (0)
; #define PG8_MMA(ai, bj, At, Bt) do { __builtin_amdgcn_s_setprio(1); _Pragma("unroll") for (int m = 0; m < 4; ++m) _Pragma("unroll") for (int n = 0; n < 2; ++n) _Pragma("unroll") for (int k = 0; k < 2; ++k) \
;         acc[ai][bj][m][n] = __builtin_amdgcn_mfma_f32_16x16x32_bf16(Bt[n][k], At[m][k], acc[ai][bj][m][n], 0, 0, 0); __builtin_amdgcn_s_setprio(0); } while (0)
; #define PG8_WAIT_V(n) asm volatile("s_waitcnt vmcnt(" #n ")" ::: "memory")
; #define PG8_WAIT_L(n) asm volatile("s_waitcnt lgkmcnt(" #n ")" ::: "memory")
; #define PG8_BAR __builtin_amdgcn_s_barrier()
; #define PG8_SCHED __builtin_amdgcn_sched_barrier(0)
; template <class Epi, class Sched>
; __device__ __forceinline__ void gemm_phase(PG8_LAS unsigned char* lds, const Gemm g, const Sched& S, const Epi& E) {
;     ...
;             PG8_LDB(B0, 0, 0); PG8_LDB(B1, 0, 1); PG8_SCHED; PG8_LDA(At, 0, 0); PG8_STAGE(PG8_SA(1, 1), a1 + hstepA, voffA);
;             PG8_WAIT_V(8); PG8_WAIT_L(0); PG8_BAR; PG8_MMA(0, 0, At, B0); PG8_MMA(0, 1, At, B1); PG8_BAR; PG8_SCHED;
;             PG8_LDA(At, 0, 1); PG8_STAGE(PG8_SB(0, 0), b2, voffB); PG8_STAGE(PG8_SB(0, 1), b2 + hstepB, voffB); PG8_STAGE(PG8_SA(0, 0), a2, voffA);
;             PG8_WAIT_V(8); PG8_WAIT_L(0); PG8_BAR; PG8_MMA(1, 0, At, B0); PG8_MMA(1, 1, At, B1); PG8_BAR; PG8_SCHED;
.LBB0_60:
	s_add_i32 s8, s7, 2
	s_add_u32 s9, s28, 0x80
	s_addc_u32 s10, s29, 0
	s_add_i32 s44, 0, 0x10000
	s_cmp_eq_u32 s91, s7
	s_cselect_b32 s39, s13, s10
	s_cselect_b32 s38, s12, s9
	s_cselect_b32 s11, s67, s6
	s_cselect_b32 s10, s66, s5
	s_add_i32 s7, 0, 0x14000
	v_add_u32_e32 v142, s44, v192
	v_add_u32_e32 v158, s7, v192
	ds_read_b128 v[130:133], v142
	ds_read_b128 v[134:137], v142 offset:1024
	ds_read_b128 v[138:141], v142 offset:2048
	ds_read_b128 v[142:145], v142 offset:3072
	ds_read_b128 v[180:183], v194
	ds_read_b128 v[184:187], v194 offset:1024
	ds_read_b128 v[188:191], v194 offset:2048
	ds_read_b128 v[196:199], v194 offset:3072
	ds_read_b128 v[200:203], v194 offset:4096
	ds_read_b128 v[216:219], v194 offset:5120
	ds_read_b128 v[220:223], v194 offset:6144
	ds_read_b128 v[224:227], v194 offset:7168
	ds_read_b128 v[146:149], v158
	ds_read_b128 v[150:153], v158 offset:1024
	ds_read_b128 v[154:157], v158 offset:2048
	ds_read_b128 v[158:161], v158 offset:3072
	v_lshl_add_u64 v[168:169], s[28:29], 0, v[176:177]
	s_add_i32 m0, s84, 0xc000
	global_load_lds_dwordx4 v[168:169], off
	v_lshl_add_u64 v[168:169], s[28:29], 0, v[178:179]
	s_add_i32 m0, s84, 0xe000
	s_nop 0
	global_load_lds_dwordx4 v[168:169], off
	s_waitcnt vmcnt(8)
	s_waitcnt lgkmcnt(4)
	s_barrier
	s_setprio 1
	s_waitcnt lgkmcnt(4)
	v_mfma_f32_16x16x32_bf16 v[126:129], v[130:133], v[180:183], v[126:129]
	v_mfma_f32_16x16x32_bf16 v[122:125], v[138:141], v[180:183], v[122:125]
	v_mfma_f32_16x16x32_bf16 v[114:117], v[130:133], v[188:191], v[114:117]
	v_mfma_f32_16x16x32_bf16 v[106:109], v[138:141], v[188:191], v[106:109]
	v_mfma_f32_16x16x32_bf16 v[94:97], v[130:133], v[200:203], v[94:97]
	v_mfma_f32_16x16x32_bf16 v[90:93], v[138:141], v[200:203], v[90:93]
	v_mfma_f32_16x16x32_bf16 v[82:85], v[130:133], v[220:223], v[82:85]
	v_mfma_f32_16x16x32_bf16 v[74:77], v[138:141], v[220:223], v[74:77]
	v_mfma_f32_16x16x32_bf16 v[126:129], v[134:137], v[184:187], v[126:129]
	v_mfma_f32_16x16x32_bf16 v[122:125], v[142:145], v[184:187], v[122:125]
	v_mfma_f32_16x16x32_bf16 v[114:117], v[134:137], v[196:199], v[114:117]
	v_mfma_f32_16x16x32_bf16 v[106:109], v[142:145], v[196:199], v[106:109]
	v_mfma_f32_16x16x32_bf16 v[94:97], v[134:137], v[216:219], v[94:97]
	v_mfma_f32_16x16x32_bf16 v[90:93], v[142:145], v[216:219], v[90:93]
	v_mfma_f32_16x16x32_bf16 v[82:85], v[134:137], v[224:227], v[82:85]
	v_mfma_f32_16x16x32_bf16 v[74:77], v[142:145], v[224:227], v[74:77]
	s_setprio 0
	s_setprio 1
	s_waitcnt lgkmcnt(0)
	v_mfma_f32_16x16x32_bf16 v[118:121], v[146:149], v[180:183], v[118:121]
	v_mfma_f32_16x16x32_bf16 v[110:113], v[154:157], v[180:183], v[110:113]
	v_mfma_f32_16x16x32_bf16 v[102:105], v[146:149], v[188:191], v[102:105]
	v_mfma_f32_16x16x32_bf16 v[98:101], v[154:157], v[188:191], v[98:101]
	v_mfma_f32_16x16x32_bf16 v[86:89], v[146:149], v[200:203], v[86:89]
	v_mfma_f32_16x16x32_bf16 v[78:81], v[154:157], v[200:203], v[78:81]
	v_mfma_f32_16x16x32_bf16 v[70:73], v[146:149], v[220:223], v[70:73]
	v_mfma_f32_16x16x32_bf16 v[66:69], v[154:157], v[220:223], v[66:69]
	v_mfma_f32_16x16x32_bf16 v[118:121], v[150:153], v[184:187], v[118:121]
	v_mfma_f32_16x16x32_bf16 v[110:113], v[158:161], v[184:187], v[110:113]
	v_mfma_f32_16x16x32_bf16 v[102:105], v[150:153], v[196:199], v[102:105]
	v_mfma_f32_16x16x32_bf16 v[98:101], v[158:161], v[196:199], v[98:101]
	v_mfma_f32_16x16x32_bf16 v[86:89], v[150:153], v[216:219], v[86:89]
	v_mfma_f32_16x16x32_bf16 v[78:81], v[158:161], v[216:219], v[78:81]
	v_mfma_f32_16x16x32_bf16 v[70:73], v[150:153], v[224:227], v[70:73]
	v_mfma_f32_16x16x32_bf16 v[66:69], v[158:161], v[224:227], v[66:69]
	s_setprio 0
	s_barrier
	s_add_i32 s9, s44, s83
	v_lshl_add_u64 v[168:169], s[10:11], 0, v[0:1]
	s_mov_b32 m0, s9
	ds_read_b128 v[180:183], v194 offset:16384
	ds_read_b128 v[184:187], v194 offset:17408
	ds_read_b128 v[188:191], v194 offset:18432
	ds_read_b128 v[196:199], v194 offset:19456
	ds_read_b128 v[200:203], v194 offset:20480
	ds_read_b128 v[216:219], v194 offset:21504
	ds_read_b128 v[220:223], v194 offset:22528
	ds_read_b128 v[224:227], v194 offset:23552
	global_load_lds_dwordx4 v[168:169], off
	s_add_i32 m0, s9, 0x2000
	v_lshl_add_u64 v[204:205], s[10:11], 0, v[174:175]
	s_add_u32 s10, s10, s20
	s_addc_u32 s11, s11, 0
	s_add_i32 s7, s7, s83
	global_load_lds_dwordx4 v[204:205], off
	v_lshl_add_u64 v[228:229], s[10:11], 0, v[0:1]
	s_mov_b32 m0, s7
	v_lshl_add_u64 v[230:231], s[10:11], 0, v[174:175]
	global_load_lds_dwordx4 v[228:229], off
	s_add_i32 m0, s7, 0x2000
	v_lshl_add_u64 v[232:233], s[38:39], 0, v[170:171]
	global_load_lds_dwordx4 v[230:231], off
	s_mov_b32 m0, s84
	v_lshl_add_u64 v[234:235], s[38:39], 0, v[172:173]
	global_load_lds_dwordx4 v[232:233], off
	s_mov_b32 m0, s85
	s_nop 0
	global_load_lds_dwordx4 v[234:235], off
	s_waitcnt vmcnt(8)
	s_waitcnt lgkmcnt(0)
	s_barrier
; #define PG8_STAGE(bufoff, gbase, voff) do { _Pragma("unroll") for (int _i = 0; _i < 2; ++_i) \
;         __builtin_amdgcn_global_load_lds((const unsigned*)((const char*)(gbase) + (voff)[_i]), (PG8_LAS unsigned*)(lds + (bufoff) + ldsw + _i * 8192), 16, 0, 0); } while (0)
; #define PG8_LDA(dst, b, h) do { _Pragma("unroll") for (int m = 0; m < 4; ++m) _Pragma("unroll") for (int k = 0; k < 2; ++k) dst[m][k] = *(const PG8_LAS bf16x8*)(lds + PG8_SA(b, h) + aoff + m * 2048 + k * 1024); } while (0)
; #define PG8_LDB(dst, b, h) do { _Pragma("unroll") for (int n = 0; n < 2; ++n) _Pragma("unroll") for (int k = 0; k < 2; ++k) dst[n][k] = *(const PG8_LAS bf16x8*)(lds + PG8_SB(b, h) + boff + n * 2048 + k * 1024); } while (0)
; #define PG8_MMA(ai, bj, At, Bt) do { __builtin_amdgcn_s_setprio(1); _Pragma("unroll") for (int m = 0; m < 4; ++m) _Pragma("unroll") for (int n = 0; n < 2; ++n) _Pragma("unroll") for (int k = 0; k < 2; ++k) \
;         acc[ai][bj][m][n] = __builtin_amdgcn_mfma_f32_16x16x32_bf16(Bt[n][k], At[m][k], acc[ai][bj][m][n], 0, 0, 0); __builtin_amdgcn_s_setprio(0); } while (0)
; #define PG8_WAIT_V(n) asm volatile("s_waitcnt vmcnt(" #n ")" ::: "memory")
; #define PG8_WAIT_L(n) asm volatile("s_waitcnt lgkmcnt(" #n ")" ::: "memory")
; #define PG8_BAR __builtin_amdgcn_s_barrier()
; #define PG8_SCHED __builtin_amdgcn_sched_barrier(0)
; template <class Epi, class Sched>
; __device__ __forceinline__ void gemm_phase(PG8_LAS unsigned char* lds, const Gemm g, const Sched& S, const Epi& E) {
;     ...
;             PG8_WAIT_V(8); PG8_WAIT_L(0); PG8_BAR; PG8_MMA(1, 0, At, B0); PG8_MMA(1, 1, At, B1); PG8_BAR; PG8_SCHED;
;             PG8_LDB(B0, 1, 0); PG8_LDB(B1, 1, 1); PG8_SCHED; PG8_LDA(At, 1, 0); PG8_STAGE(PG8_SA(0, 1), a2 + hstepA, voffA);
;             PG8_WAIT_V(8); PG8_WAIT_L(0); PG8_BAR; PG8_MMA(0, 0, At, B0); PG8_MMA(0, 1, At, B1); PG8_BAR; PG8_SCHED;
	s_setprio 1
	s_waitcnt lgkmcnt(0)
	v_mfma_f32_16x16x32_bf16 v[62:65], v[130:133], v[180:183], v[62:65]
	v_mfma_f32_16x16x32_bf16 v[58:61], v[138:141], v[180:183], v[58:61]
	v_mfma_f32_16x16x32_bf16 v[50:53], v[130:133], v[188:191], v[50:53]
	v_mfma_f32_16x16x32_bf16 v[42:45], v[138:141], v[188:191], v[42:45]
	v_mfma_f32_16x16x32_bf16 v[30:33], v[130:133], v[200:203], v[30:33]
	v_mfma_f32_16x16x32_bf16 v[26:29], v[138:141], v[200:203], v[26:29]
	v_mfma_f32_16x16x32_bf16 v[18:21], v[130:133], v[220:223], v[18:21]
	v_mfma_f32_16x16x32_bf16 v[10:13], v[138:141], v[220:223], v[10:13]
	v_mfma_f32_16x16x32_bf16 v[62:65], v[134:137], v[184:187], v[62:65]
	v_mfma_f32_16x16x32_bf16 v[58:61], v[142:145], v[184:187], v[58:61]
	v_mfma_f32_16x16x32_bf16 v[50:53], v[134:137], v[196:199], v[50:53]
	v_mfma_f32_16x16x32_bf16 v[42:45], v[142:145], v[196:199], v[42:45]
	v_mfma_f32_16x16x32_bf16 v[30:33], v[134:137], v[216:219], v[30:33]
	v_mfma_f32_16x16x32_bf16 v[26:29], v[142:145], v[216:219], v[26:29]
	v_mfma_f32_16x16x32_bf16 v[18:21], v[134:137], v[224:227], v[18:21]
	v_mfma_f32_16x16x32_bf16 v[10:13], v[142:145], v[224:227], v[10:13]
	s_setprio 0
	s_setprio 1
	v_mfma_f32_16x16x32_bf16 v[54:57], v[146:149], v[180:183], v[54:57]
	v_mfma_f32_16x16x32_bf16 v[46:49], v[154:157], v[180:183], v[46:49]
	v_mfma_f32_16x16x32_bf16 v[38:41], v[146:149], v[188:191], v[38:41]
	v_mfma_f32_16x16x32_bf16 v[34:37], v[154:157], v[188:191], v[34:37]
	v_mfma_f32_16x16x32_bf16 v[22:25], v[146:149], v[200:203], v[22:25]
	v_mfma_f32_16x16x32_bf16 v[14:17], v[154:157], v[200:203], v[14:17]
	v_mfma_f32_16x16x32_bf16 v[6:9], v[146:149], v[220:223], v[6:9]
	v_mfma_f32_16x16x32_bf16 v[2:5], v[154:157], v[220:223], v[2:5]
	v_mfma_f32_16x16x32_bf16 v[54:57], v[150:153], v[184:187], v[54:57]
	v_mfma_f32_16x16x32_bf16 v[46:49], v[158:161], v[184:187], v[46:49]
	v_mfma_f32_16x16x32_bf16 v[38:41], v[150:153], v[196:199], v[38:41]
	v_mfma_f32_16x16x32_bf16 v[34:37], v[158:161], v[196:199], v[34:37]
	v_mfma_f32_16x16x32_bf16 v[22:25], v[150:153], v[216:219], v[22:25]
	v_mfma_f32_16x16x32_bf16 v[14:17], v[158:161], v[216:219], v[14:17]
	v_mfma_f32_16x16x32_bf16 v[6:9], v[150:153], v[224:227], v[6:9]
	v_mfma_f32_16x16x32_bf16 v[2:5], v[158:161], v[224:227], v[2:5]
	s_setprio 0
	s_barrier
	s_add_i32 s7, 0, 0x18000
	s_add_i32 s9, 0, 0x1c000
	v_add_u32_e32 v142, s7, v192
	v_add_u32_e32 v158, s9, v192
	ds_read_b128 v[130:133], v142
	ds_read_b128 v[134:137], v142 offset:1024
	ds_read_b128 v[138:141], v142 offset:2048
	ds_read_b128 v[142:145], v142 offset:3072
	ds_read_b128 v[180:183], v194 offset:32768
	ds_read_b128 v[184:187], v194 offset:33792
	ds_read_b128 v[188:191], v194 offset:34816
	ds_read_b128 v[196:199], v194 offset:35840
	ds_read_b128 v[200:203], v194 offset:36864
	ds_read_b128 v[216:219], v194 offset:37888
	ds_read_b128 v[220:223], v194 offset:38912
	ds_read_b128 v[224:227], v194 offset:39936
	ds_read_b128 v[146:149], v158
	ds_read_b128 v[150:153], v158 offset:1024
	ds_read_b128 v[154:157], v158 offset:2048
	ds_read_b128 v[158:161], v158 offset:3072
	s_add_u32 s10, s38, s20
	s_addc_u32 s11, s39, 0
	s_mov_b32 m0, s86
	v_lshl_add_u64 v[236:237], s[10:11], 0, v[170:171]
	global_load_lds_dwordx4 v[236:237], off
	v_lshl_add_u64 v[236:237], s[10:11], 0, v[172:173]
	s_mov_b32 m0, s87
	s_nop 0
	global_load_lds_dwordx4 v[236:237], off
	s_waitcnt vmcnt(8)
	s_waitcnt lgkmcnt(4)
	s_barrier
	s_setprio 1
	s_waitcnt lgkmcnt(4)
	v_mfma_f32_16x16x32_bf16 v[126:129], v[130:133], v[180:183], v[126:129]
	v_mfma_f32_16x16x32_bf16 v[122:125], v[138:141], v[180:183], v[122:125]
	v_mfma_f32_16x16x32_bf16 v[114:117], v[130:133], v[188:191], v[114:117]
	v_mfma_f32_16x16x32_bf16 v[106:109], v[138:141], v[188:191], v[106:109]
	v_mfma_f32_16x16x32_bf16 v[94:97], v[130:133], v[200:203], v[94:97]
	v_mfma_f32_16x16x32_bf16 v[90:93], v[138:141], v[200:203], v[90:93]
	v_mfma_f32_16x16x32_bf16 v[82:85], v[130:133], v[220:223], v[82:85]
	v_mfma_f32_16x16x32_bf16 v[74:77], v[138:141], v[220:223], v[74:77]
	v_mfma_f32_16x16x32_bf16 v[126:129], v[134:137], v[184:187], v[126:129]
	v_mfma_f32_16x16x32_bf16 v[122:125], v[142:145], v[184:187], v[122:125]
	v_mfma_f32_16x16x32_bf16 v[114:117], v[134:137], v[196:199], v[114:117]
	v_mfma_f32_16x16x32_bf16 v[106:109], v[142:145], v[196:199], v[106:109]
	v_mfma_f32_16x16x32_bf16 v[94:97], v[134:137], v[216:219], v[94:97]
	v_mfma_f32_16x16x32_bf16 v[90:93], v[142:145], v[216:219], v[90:93]
	v_mfma_f32_16x16x32_bf16 v[82:85], v[134:137], v[224:227], v[82:85]
	v_mfma_f32_16x16x32_bf16 v[74:77], v[142:145], v[224:227], v[74:77]
	s_setprio 0
	s_setprio 1
	s_waitcnt lgkmcnt(0)
	v_mfma_f32_16x16x32_bf16 v[118:121], v[146:149], v[180:183], v[118:121]
	v_mfma_f32_16x16x32_bf16 v[110:113], v[154:157], v[180:183], v[110:113]
	v_mfma_f32_16x16x32_bf16 v[102:105], v[146:149], v[188:191], v[102:105]
	v_mfma_f32_16x16x32_bf16 v[98:101], v[154:157], v[188:191], v[98:101]
	v_mfma_f32_16x16x32_bf16 v[86:89], v[146:149], v[200:203], v[86:89]
	v_mfma_f32_16x16x32_bf16 v[78:81], v[154:157], v[200:203], v[78:81]
	v_mfma_f32_16x16x32_bf16 v[70:73], v[146:149], v[220:223], v[70:73]
	v_mfma_f32_16x16x32_bf16 v[66:69], v[154:157], v[220:223], v[66:69]
	v_mfma_f32_16x16x32_bf16 v[118:121], v[150:153], v[184:187], v[118:121]
	v_mfma_f32_16x16x32_bf16 v[110:113], v[158:161], v[184:187], v[110:113]
	v_mfma_f32_16x16x32_bf16 v[102:105], v[150:153], v[196:199], v[102:105]
	v_mfma_f32_16x16x32_bf16 v[98:101], v[158:161], v[196:199], v[98:101]
	v_mfma_f32_16x16x32_bf16 v[86:89], v[150:153], v[216:219], v[86:89]
	v_mfma_f32_16x16x32_bf16 v[78:81], v[158:161], v[216:219], v[78:81]
	v_mfma_f32_16x16x32_bf16 v[70:73], v[150:153], v[224:227], v[70:73]
	v_mfma_f32_16x16x32_bf16 v[66:69], v[158:161], v[224:227], v[66:69]
	s_setprio 0
	s_barrier
; #define PG8_STAGE(bufoff, gbase, voff) do { _Pragma("unroll") for (int _i = 0; _i < 2; ++_i) \
;         __builtin_amdgcn_global_load_lds((const unsigned*)((const char*)(gbase) + (voff)[_i]), (PG8_LAS unsigned*)(lds + (bufoff) + ldsw + _i * 8192), 16, 0, 0); } while (0)
; #define PG8_LDA(dst, b, h) do { _Pragma("unroll") for (int m = 0; m < 4; ++m) _Pragma("unroll") for (int k = 0; k < 2; ++k) dst[m][k] = *(const PG8_LAS bf16x8*)(lds + PG8_SA(b, h) + aoff + m * 2048 + k * 1024); } while (0)
; #define PG8_MMA(ai, bj, At, Bt) do { __builtin_amdgcn_s_setprio(1); _Pragma("unroll") for (int m = 0; m < 4; ++m) _Pragma("unroll") for (int n = 0; n < 2; ++n) _Pragma("unroll") for (int k = 0; k < 2; ++k) \
;         acc[ai][bj][m][n] = __builtin_amdgcn_mfma_f32_16x16x32_bf16(Bt[n][k], At[m][k], acc[ai][bj][m][n], 0, 0, 0); __builtin_amdgcn_s_setprio(0); } while (0)
; #define PG8_WAIT_V(n) asm volatile("s_waitcnt vmcnt(" #n ")" ::: "memory")
; #define PG8_WAIT_L(n) asm volatile("s_waitcnt lgkmcnt(" #n ")" ::: "memory")
; #define PG8_BAR __builtin_amdgcn_s_barrier()
; #define PG8_SCHED __builtin_amdgcn_sched_barrier(0)
; template <class Epi, class Sched>
; __device__ __forceinline__ void gemm_phase(PG8_LAS unsigned char* lds, const Gemm g, const Sched& S, const Epi& E) {
;     ...
;             PG8_LDA(At, 1, 1); PG8_STAGE(PG8_SB(1, 0), b3, voffB); PG8_STAGE(PG8_SB(1, 1), b3 + hstepB, voffB); PG8_STAGE(PG8_SA(1, 0), a3, voffA);
;             PG8_WAIT_V(8); PG8_WAIT_L(0); PG8_BAR; PG8_MMA(1, 0, At, B0); PG8_MMA(1, 1, At, B1); PG8_BAR; PG8_SCHED;
;         }
	s_add_i32 s7, s7, s83
	v_lshl_add_u64 v[168:169], v[168:169], 0, s[22:23]
	s_mov_b32 m0, s7
	ds_read_b128 v[180:183], v194 offset:49152
	ds_read_b128 v[184:187], v194 offset:50176
	ds_read_b128 v[188:191], v194 offset:51200
	ds_read_b128 v[196:199], v194 offset:52224
	ds_read_b128 v[200:203], v194 offset:53248
	ds_read_b128 v[216:219], v194 offset:54272
	ds_read_b128 v[220:223], v194 offset:55296
	ds_read_b128 v[224:227], v194 offset:56320
	global_load_lds_dwordx4 v[168:169], off
	v_lshl_add_u64 v[168:169], v[204:205], 0, s[22:23]
	s_add_i32 m0, s7, 0x2000
	s_add_i32 s7, s9, s83
	global_load_lds_dwordx4 v[168:169], off
	v_lshl_add_u64 v[168:169], v[228:229], 0, s[22:23]
	s_mov_b32 m0, s7
	s_nop 0
	global_load_lds_dwordx4 v[168:169], off
	v_lshl_add_u64 v[168:169], v[230:231], 0, s[22:23]
	s_add_i32 m0, s7, 0x2000
	s_nop 0
	global_load_lds_dwordx4 v[168:169], off
	v_lshl_add_u64 v[168:169], v[232:233], 0, s[22:23]
	s_mov_b32 m0, s88
	s_nop 0
	global_load_lds_dwordx4 v[168:169], off
	v_lshl_add_u64 v[168:169], v[234:235], 0, s[22:23]
	s_mov_b32 m0, s89
	s_nop 0
	global_load_lds_dwordx4 v[168:169], off
	s_waitcnt vmcnt(8)
	s_waitcnt lgkmcnt(0)
	s_barrier
	s_setprio 1
	s_waitcnt lgkmcnt(0)
	v_mfma_f32_16x16x32_bf16 v[62:65], v[130:133], v[180:183], v[62:65]
	v_mfma_f32_16x16x32_bf16 v[58:61], v[138:141], v[180:183], v[58:61]
	v_mfma_f32_16x16x32_bf16 v[50:53], v[130:133], v[188:191], v[50:53]
	v_mfma_f32_16x16x32_bf16 v[42:45], v[138:141], v[188:191], v[42:45]
	v_mfma_f32_16x16x32_bf16 v[30:33], v[130:133], v[200:203], v[30:33]
	v_mfma_f32_16x16x32_bf16 v[26:29], v[138:141], v[200:203], v[26:29]
	v_mfma_f32_16x16x32_bf16 v[18:21], v[130:133], v[220:223], v[18:21]
	v_mfma_f32_16x16x32_bf16 v[10:13], v[138:141], v[220:223], v[10:13]
	v_mfma_f32_16x16x32_bf16 v[62:65], v[134:137], v[184:187], v[62:65]
	v_mfma_f32_16x16x32_bf16 v[58:61], v[142:145], v[184:187], v[58:61]
	v_mfma_f32_16x16x32_bf16 v[50:53], v[134:137], v[196:199], v[50:53]
	v_mfma_f32_16x16x32_bf16 v[42:45], v[142:145], v[196:199], v[42:45]
	v_mfma_f32_16x16x32_bf16 v[30:33], v[134:137], v[216:219], v[30:33]
	v_mfma_f32_16x16x32_bf16 v[26:29], v[142:145], v[216:219], v[26:29]
	v_mfma_f32_16x16x32_bf16 v[18:21], v[134:137], v[224:227], v[18:21]
	v_mfma_f32_16x16x32_bf16 v[10:13], v[142:145], v[224:227], v[10:13]
	s_setprio 0
	s_setprio 1
	v_mfma_f32_16x16x32_bf16 v[54:57], v[146:149], v[180:183], v[54:57]
	v_mfma_f32_16x16x32_bf16 v[46:49], v[154:157], v[180:183], v[46:49]
	v_mfma_f32_16x16x32_bf16 v[38:41], v[146:149], v[188:191], v[38:41]
	v_mfma_f32_16x16x32_bf16 v[34:37], v[154:157], v[188:191], v[34:37]
	v_mfma_f32_16x16x32_bf16 v[22:25], v[146:149], v[200:203], v[22:25]
	v_mfma_f32_16x16x32_bf16 v[14:17], v[154:157], v[200:203], v[14:17]
	v_mfma_f32_16x16x32_bf16 v[6:9], v[146:149], v[220:223], v[6:9]
	v_mfma_f32_16x16x32_bf16 v[2:5], v[154:157], v[220:223], v[2:5]
	v_mfma_f32_16x16x32_bf16 v[54:57], v[150:153], v[184:187], v[54:57]
	v_mfma_f32_16x16x32_bf16 v[46:49], v[158:161], v[184:187], v[46:49]
	v_mfma_f32_16x16x32_bf16 v[38:41], v[150:153], v[196:199], v[38:41]
	v_mfma_f32_16x16x32_bf16 v[34:37], v[158:161], v[196:199], v[34:37]
	v_mfma_f32_16x16x32_bf16 v[22:25], v[150:153], v[216:219], v[22:25]
	v_mfma_f32_16x16x32_bf16 v[14:17], v[158:161], v[216:219], v[14:17]
	v_mfma_f32_16x16x32_bf16 v[6:9], v[150:153], v[224:227], v[6:9]
	v_mfma_f32_16x16x32_bf16 v[2:5], v[158:161], v[224:227], v[2:5]
	s_setprio 0
	s_barrier
	s_add_u32 s28, s28, 0x100
	s_addc_u32 s29, s29, 0
	s_add_u32 s5, s5, 0x100
	s_addc_u32 s6, s6, 0
	s_cmp_ge_u32 s8, s90
	s_mov_b32 s7, s8
	s_cbranch_scc0 .LBB0_60
	s_and_b64 vcc, exec, s[64:65]
	s_cbranch_vccz .LBB0_63
	s_barrier

; #define PG8_STAGE(bufoff, gbase, voff) do { _Pragma("unroll") for (int _i = 0; _i < 2; ++_i) \
;         __builtin_amdgcn_global_load_lds((const unsigned*)((const char*)(gbase) + (voff)[_i]), (PG8_LAS unsigned*)(lds + (bufoff) + ldsw + _i * 8192), 16, 0, 0); } while (0)
; #define PG8_LDA(dst, b, h) do { _Pragma("unroll") for (int m = 0; m < 4; ++m) _Pragma("unroll") for (int k = 0; k < 2; ++k) dst[m][k] = *(const PG8_LAS bf16x8*)(lds + PG8_SA(b, h) + aoff + m * 2048 + k * 1024); } while (0)
; #define PG8_LDB(dst, b, h) do { _Pragma("unroll") for (int n = 0; n < 2; ++n) _Pragma("unroll") for (int k = 0; k < 2; ++k) dst[n][k] = *(const PG8_LAS bf16x8*)(lds + PG8_SB(b, h) + boff + n * 2048 + k * 1024); } while (0)
; #define PG8_MMA(ai, bj, At, Bt) do { __builtin_amdgcn_s_setprio(1); _Pragma("unroll") for (int m = 0; m < 4; ++m) _Pragma("unroll") for (int n = 0; n < 2; ++n) _Pragma("unroll") for (int k = 0; k < 2; ++k) \
;         acc[ai][bj][m][n] = __builtin_amdgcn_mfma_f32_16x16x32_bf16(Bt[n][k], At[m][k], acc[ai][bj][m][n], 0, 0, 0); __builtin_amdgcn_s_setprio(0); } while (0)
; #define PG8_WAIT_V(n) asm volatile("s_waitcnt vmcnt(" #n ")" ::: "memory")
; #define PG8_WAIT_L(n) asm volatile("s_waitcnt lgkmcnt(" #n ")" ::: "memory")
; #define PG8_BAR __builtin_amdgcn_s_barrier()
; #define PG8_SCHED __builtin_amdgcn_sched_barrier(0)
; template <class Epi, class Sched>
; __device__ __forceinline__ void gemm_phase(PG8_LAS unsigned char* lds, const Gemm g, const Sched& S, const Epi& E) {
;     ...
;             PG8_LDB(B0, 0, 0); PG8_LDB(B1, 0, 1); PG8_SCHED; PG8_LDA(At, 0, 0); PG8_STAGE(PG8_SA(1, 1), a1 + hstepA, voffA);
;             PG8_WAIT_V(8); PG8_WAIT_L(0); PG8_BAR; PG8_MMA(0, 0, At, B0); PG8_MMA(0, 1, At, B1); PG8_BAR; PG8_SCHED;
;             PG8_LDA(At, 0, 1); PG8_STAGE(PG8_SB(0, 0), b2, voffB); PG8_STAGE(PG8_SB(0, 1), b2 + hstepB, voffB); PG8_STAGE(PG8_SA(0, 0), a2, voffA);
;             PG8_WAIT_V(8); PG8_WAIT_L(0); PG8_BAR; PG8_MMA(1, 0, At, B0); PG8_MMA(1, 1, At, B1); PG8_BAR; PG8_SCHED;
.LBB0_132:
	s_add_u32 s10, s28, 0xfff80080
	s_addc_u32 s11, s29, -1
	s_add_i32 s76, 0, 0x10000
	s_cmp_eq_u32 s9, 12
	s_cselect_b32 vcc_hi, s67, s11
	s_cselect_b32 vcc_lo, s97, s10
	v_add_u32_e32 v0, s76, v216
	s_cselect_b32 s43, s65, s8
	s_cselect_b32 s42, s6, s7
	s_add_i32 s57, 0, 0x14000
	ds_read_b128 v[66:69], v0
	ds_read_b128 v[78:81], v0 offset:1024
	ds_read_b128 v[90:93], v0 offset:2048
	ds_read_b128 v[102:105], v0 offset:3072
	ds_read_b128 v[182:185], v218
	ds_read_b128 v[186:189], v218 offset:1024
	ds_read_b128 v[190:193], v218 offset:2048
	ds_read_b128 v[194:197], v218 offset:3072
	ds_read_b128 v[198:201], v218 offset:4096
	ds_read_b128 v[202:205], v218 offset:5120
	ds_read_b128 v[220:223], v218 offset:6144
	ds_read_b128 v[224:227], v218 offset:7168
	v_add_u32_e32 v0, s57, v216
	ds_read_b128 v[146:149], v0
	ds_read_b128 v[150:153], v0 offset:1024
	ds_read_b128 v[154:157], v0 offset:2048
	ds_read_b128 v[158:161], v0 offset:3072
	v_lshl_add_u64 v[168:169], s[28:29], 0, v[178:179]
	s_add_i32 m0, s88, 0xc000
	global_load_lds_dwordx4 v[168:169], off
	v_lshl_add_u64 v[168:169], s[28:29], 0, v[180:181]
	s_add_i32 m0, s88, 0xe000
	s_nop 0
	global_load_lds_dwordx4 v[168:169], off
	s_waitcnt vmcnt(8)
	s_waitcnt lgkmcnt(4)
	s_barrier
	s_setprio 1
	s_waitcnt lgkmcnt(4)
	v_mfma_f32_16x16x32_bf16 v[142:145], v[66:69], v[182:185], v[142:145]
	v_mfma_f32_16x16x32_bf16 v[138:141], v[90:93], v[182:185], v[138:141]
	v_mfma_f32_16x16x32_bf16 v[134:137], v[66:69], v[190:193], v[134:137]
	v_mfma_f32_16x16x32_bf16 v[130:133], v[90:93], v[190:193], v[130:133]
	v_mfma_f32_16x16x32_bf16 v[126:129], v[66:69], v[198:201], v[126:129]
	v_mfma_f32_16x16x32_bf16 v[122:125], v[90:93], v[198:201], v[122:125]
	v_mfma_f32_16x16x32_bf16 v[118:121], v[66:69], v[220:223], v[118:121]
	v_mfma_f32_16x16x32_bf16 v[114:117], v[90:93], v[220:223], v[114:117]
	v_mfma_f32_16x16x32_bf16 v[142:145], v[78:81], v[186:189], v[142:145]
	v_mfma_f32_16x16x32_bf16 v[138:141], v[102:105], v[186:189], v[138:141]
	v_mfma_f32_16x16x32_bf16 v[134:137], v[78:81], v[194:197], v[134:137]
	v_mfma_f32_16x16x32_bf16 v[130:133], v[102:105], v[194:197], v[130:133]
	v_mfma_f32_16x16x32_bf16 v[126:129], v[78:81], v[202:205], v[126:129]
	v_mfma_f32_16x16x32_bf16 v[122:125], v[102:105], v[202:205], v[122:125]
	v_mfma_f32_16x16x32_bf16 v[118:121], v[78:81], v[224:227], v[118:121]
	v_mfma_f32_16x16x32_bf16 v[114:117], v[102:105], v[224:227], v[114:117]
	s_setprio 0
	s_setprio 1
	s_waitcnt lgkmcnt(0)
	v_mfma_f32_16x16x32_bf16 v[62:65], v[146:149], v[182:185], v[62:65]
	v_mfma_f32_16x16x32_bf16 v[58:61], v[154:157], v[182:185], v[58:61]
	v_mfma_f32_16x16x32_bf16 v[54:57], v[146:149], v[190:193], v[54:57]
	v_mfma_f32_16x16x32_bf16 v[50:53], v[154:157], v[190:193], v[50:53]
	v_mfma_f32_16x16x32_bf16 v[46:49], v[146:149], v[198:201], v[46:49]
	v_mfma_f32_16x16x32_bf16 v[42:45], v[154:157], v[198:201], v[42:45]
	v_mfma_f32_16x16x32_bf16 v[38:41], v[146:149], v[220:223], v[38:41]
	v_mfma_f32_16x16x32_bf16 v[34:37], v[154:157], v[220:223], v[34:37]
	v_mfma_f32_16x16x32_bf16 v[62:65], v[150:153], v[186:189], v[62:65]
	v_mfma_f32_16x16x32_bf16 v[58:61], v[158:161], v[186:189], v[58:61]
	v_mfma_f32_16x16x32_bf16 v[54:57], v[150:153], v[194:197], v[54:57]
	v_mfma_f32_16x16x32_bf16 v[50:53], v[158:161], v[194:197], v[50:53]
	v_mfma_f32_16x16x32_bf16 v[46:49], v[150:153], v[202:205], v[46:49]
	v_mfma_f32_16x16x32_bf16 v[42:45], v[158:161], v[202:205], v[42:45]
	v_mfma_f32_16x16x32_bf16 v[38:41], v[150:153], v[224:227], v[38:41]
	v_mfma_f32_16x16x32_bf16 v[34:37], v[158:161], v[224:227], v[34:37]
	s_setprio 0
	s_barrier
	s_add_i32 s10, s76, s87
	v_lshl_add_u64 v[168:169], s[42:43], 0, v[174:175]
	s_mov_b32 m0, s10
	ds_read_b128 v[182:185], v218 offset:16384
	ds_read_b128 v[186:189], v218 offset:17408
	ds_read_b128 v[190:193], v218 offset:18432
	ds_read_b128 v[194:197], v218 offset:19456
	ds_read_b128 v[198:201], v218 offset:20480
	ds_read_b128 v[202:205], v218 offset:21504
	ds_read_b128 v[220:223], v218 offset:22528
	ds_read_b128 v[224:227], v218 offset:23552
	global_load_lds_dwordx4 v[168:169], off
	s_add_i32 m0, s10, 0x2000
	s_add_u32 s10, s42, 0x80000
	v_lshl_add_u64 v[228:229], s[42:43], 0, v[170:171]
	s_addc_u32 s11, s43, 0
	s_add_i32 s57, s57, s87
	global_load_lds_dwordx4 v[228:229], off
	v_lshl_add_u64 v[230:231], s[10:11], 0, v[174:175]
	s_mov_b32 m0, s57
	v_lshl_add_u64 v[232:233], vcc, 0, v[172:173]
	global_load_lds_dwordx4 v[230:231], off
	v_lshl_add_u64 v[230:231], s[10:11], 0, v[170:171]
	s_add_i32 m0, s57, 0x2000
	s_nop 0
	global_load_lds_dwordx4 v[230:231], off
	v_lshl_add_u64 v[230:231], vcc, 0, v[176:177]
	s_mov_b32 m0, s88
	s_nop 0
	global_load_lds_dwordx4 v[230:231], off
	s_mov_b32 m0, s89
	s_nop 0
	global_load_lds_dwordx4 v[232:233], off
	s_waitcnt vmcnt(8)
	s_waitcnt lgkmcnt(0)
	s_barrier
; #define PG8_STAGE(bufoff, gbase, voff) do { _Pragma("unroll") for (int _i = 0; _i < 2; ++_i) \
;         __builtin_amdgcn_global_load_lds((const unsigned*)((const char*)(gbase) + (voff)[_i]), (PG8_LAS unsigned*)(lds + (bufoff) + ldsw + _i * 8192), 16, 0, 0); } while (0)
; #define PG8_LDA(dst, b, h) do { _Pragma("unroll") for (int m = 0; m < 4; ++m) _Pragma("unroll") for (int k = 0; k < 2; ++k) dst[m][k] = *(const PG8_LAS bf16x8*)(lds + PG8_SA(b, h) + aoff + m * 2048 + k * 1024); } while (0)
; #define PG8_LDB(dst, b, h) do { _Pragma("unroll") for (int n = 0; n < 2; ++n) _Pragma("unroll") for (int k = 0; k < 2; ++k) dst[n][k] = *(const PG8_LAS bf16x8*)(lds + PG8_SB(b, h) + boff + n * 2048 + k * 1024); } while (0)
; #define PG8_MMA(ai, bj, At, Bt) do { __builtin_amdgcn_s_setprio(1); _Pragma("unroll") for (int m = 0; m < 4; ++m) _Pragma("unroll") for (int n = 0; n < 2; ++n) _Pragma("unroll") for (int k = 0; k < 2; ++k) \
;         acc[ai][bj][m][n] = __builtin_amdgcn_mfma_f32_16x16x32_bf16(Bt[n][k], At[m][k], acc[ai][bj][m][n], 0, 0, 0); __builtin_amdgcn_s_setprio(0); } while (0)
; #define PG8_WAIT_V(n) asm volatile("s_waitcnt vmcnt(" #n ")" ::: "memory")
; #define PG8_WAIT_L(n) asm volatile("s_waitcnt lgkmcnt(" #n ")" ::: "memory")
; #define PG8_BAR __builtin_amdgcn_s_barrier()
; #define PG8_SCHED __builtin_amdgcn_sched_barrier(0)
; template <class Epi, class Sched>
; __device__ __forceinline__ void gemm_phase(PG8_LAS unsigned char* lds, const Gemm g, const Sched& S, const Epi& E) {
;     ...
;             PG8_WAIT_V(8); PG8_WAIT_L(0); PG8_BAR; PG8_MMA(1, 0, At, B0); PG8_MMA(1, 1, At, B1); PG8_BAR; PG8_SCHED;
;             PG8_LDB(B0, 1, 0); PG8_LDB(B1, 1, 1); PG8_SCHED; PG8_LDA(At, 1, 0); PG8_STAGE(PG8_SA(0, 1), a2 + hstepA, voffA);
;             PG8_WAIT_V(8); PG8_WAIT_L(0); PG8_BAR; PG8_MMA(0, 0, At, B0); PG8_MMA(0, 1, At, B1); PG8_BAR; PG8_SCHED;
	s_setprio 1
	s_waitcnt lgkmcnt(0)
	v_mfma_f32_16x16x32_bf16 v[110:113], v[66:69], v[182:185], v[110:113]
	v_mfma_f32_16x16x32_bf16 v[106:109], v[90:93], v[182:185], v[106:109]
	v_mfma_f32_16x16x32_bf16 v[98:101], v[66:69], v[190:193], v[98:101]
	v_mfma_f32_16x16x32_bf16 v[94:97], v[90:93], v[190:193], v[94:97]
	v_mfma_f32_16x16x32_bf16 v[86:89], v[66:69], v[198:201], v[86:89]
	v_mfma_f32_16x16x32_bf16 v[82:85], v[90:93], v[198:201], v[82:85]
	v_mfma_f32_16x16x32_bf16 v[70:73], v[90:93], v[220:223], v[70:73]
	v_mfma_f32_16x16x32_bf16 v[110:113], v[78:81], v[186:189], v[110:113]
	v_mfma_f32_16x16x32_bf16 v[106:109], v[102:105], v[186:189], v[106:109]
	v_mfma_f32_16x16x32_bf16 v[98:101], v[78:81], v[194:197], v[98:101]
	v_mfma_f32_16x16x32_bf16 v[94:97], v[102:105], v[194:197], v[94:97]
	v_mfma_f32_16x16x32_bf16 v[86:89], v[78:81], v[202:205], v[86:89]
	v_mfma_f32_16x16x32_bf16 v[82:85], v[102:105], v[202:205], v[82:85]
	v_mfma_f32_16x16x32_bf16 v[66:69], v[66:69], v[220:223], v[74:77]
	v_mfma_f32_16x16x32_bf16 v[70:73], v[102:105], v[224:227], v[70:73]
	v_mfma_f32_16x16x32_bf16 v[66:69], v[78:81], v[224:227], v[66:69]
	s_setprio 0
	s_setprio 1
	v_mfma_f32_16x16x32_bf16 v[30:33], v[146:149], v[182:185], v[30:33]
	v_mfma_f32_16x16x32_bf16 v[26:29], v[154:157], v[182:185], v[26:29]
	v_mfma_f32_16x16x32_bf16 v[22:25], v[146:149], v[190:193], v[22:25]
	v_mfma_f32_16x16x32_bf16 v[18:21], v[154:157], v[190:193], v[18:21]
	v_mfma_f32_16x16x32_bf16 v[14:17], v[146:149], v[198:201], v[14:17]
	v_mfma_f32_16x16x32_bf16 v[10:13], v[154:157], v[198:201], v[10:13]
	v_mfma_f32_16x16x32_bf16 v[6:9], v[146:149], v[220:223], v[6:9]
	v_mfma_f32_16x16x32_bf16 v[2:5], v[154:157], v[220:223], v[2:5]
	v_mfma_f32_16x16x32_bf16 v[30:33], v[150:153], v[186:189], v[30:33]
	v_mfma_f32_16x16x32_bf16 v[26:29], v[158:161], v[186:189], v[26:29]
	v_mfma_f32_16x16x32_bf16 v[22:25], v[150:153], v[194:197], v[22:25]
	v_mfma_f32_16x16x32_bf16 v[18:21], v[158:161], v[194:197], v[18:21]
	v_mfma_f32_16x16x32_bf16 v[14:17], v[150:153], v[202:205], v[14:17]
	v_mfma_f32_16x16x32_bf16 v[10:13], v[158:161], v[202:205], v[10:13]
	v_mfma_f32_16x16x32_bf16 v[6:9], v[150:153], v[224:227], v[6:9]
	v_mfma_f32_16x16x32_bf16 v[2:5], v[158:161], v[224:227], v[2:5]
	s_setprio 0
	s_barrier
	s_add_i32 s57, 0, 0x18000
	v_add_u32_e32 v0, s57, v216
	s_add_i32 s76, 0, 0x1c000
	ds_read_b128 v[74:77], v0
	ds_read_b128 v[78:81], v0 offset:1024
	ds_read_b128 v[90:93], v0 offset:2048
	ds_read_b128 v[102:105], v0 offset:3072
	ds_read_b128 v[182:185], v218 offset:32768
	ds_read_b128 v[186:189], v218 offset:33792
	ds_read_b128 v[190:193], v218 offset:34816
	ds_read_b128 v[194:197], v218 offset:35840
	ds_read_b128 v[198:201], v218 offset:36864
	ds_read_b128 v[202:205], v218 offset:37888
	ds_read_b128 v[220:223], v218 offset:38912
	ds_read_b128 v[224:227], v218 offset:39936
	v_add_u32_e32 v0, s76, v216
	ds_read_b128 v[146:149], v0
	ds_read_b128 v[150:153], v0 offset:1024
	ds_read_b128 v[154:157], v0 offset:2048
	ds_read_b128 v[158:161], v0 offset:3072
	s_add_u32 s10, vcc_lo, 0x80000
	s_addc_u32 s11, vcc_hi, 0
	s_mov_b32 m0, s90
	v_lshl_add_u64 v[234:235], s[10:11], 0, v[176:177]
	global_load_lds_dwordx4 v[234:235], off
	v_lshl_add_u64 v[234:235], s[10:11], 0, v[172:173]
	s_mov_b32 m0, s91
	s_nop 0
	global_load_lds_dwordx4 v[234:235], off
	s_waitcnt vmcnt(8)
	s_waitcnt lgkmcnt(4)
	s_barrier
	s_setprio 1
	s_waitcnt lgkmcnt(4)
	v_mfma_f32_16x16x32_bf16 v[142:145], v[74:77], v[182:185], v[142:145]
	v_mfma_f32_16x16x32_bf16 v[138:141], v[90:93], v[182:185], v[138:141]
	v_mfma_f32_16x16x32_bf16 v[134:137], v[74:77], v[190:193], v[134:137]
	v_mfma_f32_16x16x32_bf16 v[130:133], v[90:93], v[190:193], v[130:133]
	v_mfma_f32_16x16x32_bf16 v[126:129], v[74:77], v[198:201], v[126:129]
	v_mfma_f32_16x16x32_bf16 v[122:125], v[90:93], v[198:201], v[122:125]
	v_mfma_f32_16x16x32_bf16 v[118:121], v[74:77], v[220:223], v[118:121]
	v_mfma_f32_16x16x32_bf16 v[114:117], v[90:93], v[220:223], v[114:117]
	v_mfma_f32_16x16x32_bf16 v[142:145], v[78:81], v[186:189], v[142:145]
	v_mfma_f32_16x16x32_bf16 v[138:141], v[102:105], v[186:189], v[138:141]
	v_mfma_f32_16x16x32_bf16 v[134:137], v[78:81], v[194:197], v[134:137]
	v_mfma_f32_16x16x32_bf16 v[130:133], v[102:105], v[194:197], v[130:133]
	v_mfma_f32_16x16x32_bf16 v[126:129], v[78:81], v[202:205], v[126:129]
	v_mfma_f32_16x16x32_bf16 v[122:125], v[102:105], v[202:205], v[122:125]
	v_mfma_f32_16x16x32_bf16 v[118:121], v[78:81], v[224:227], v[118:121]
	v_mfma_f32_16x16x32_bf16 v[114:117], v[102:105], v[224:227], v[114:117]
	s_setprio 0
	s_setprio 1
	s_waitcnt lgkmcnt(0)
	v_mfma_f32_16x16x32_bf16 v[62:65], v[146:149], v[182:185], v[62:65]
	v_mfma_f32_16x16x32_bf16 v[58:61], v[154:157], v[182:185], v[58:61]
	v_mfma_f32_16x16x32_bf16 v[54:57], v[146:149], v[190:193], v[54:57]
	v_mfma_f32_16x16x32_bf16 v[50:53], v[154:157], v[190:193], v[50:53]
	v_mfma_f32_16x16x32_bf16 v[46:49], v[146:149], v[198:201], v[46:49]
	v_mfma_f32_16x16x32_bf16 v[42:45], v[154:157], v[198:201], v[42:45]
	v_mfma_f32_16x16x32_bf16 v[38:41], v[146:149], v[220:223], v[38:41]
	v_mfma_f32_16x16x32_bf16 v[34:37], v[154:157], v[220:223], v[34:37]
	v_mfma_f32_16x16x32_bf16 v[62:65], v[150:153], v[186:189], v[62:65]
	v_mfma_f32_16x16x32_bf16 v[58:61], v[158:161], v[186:189], v[58:61]
	v_mfma_f32_16x16x32_bf16 v[54:57], v[150:153], v[194:197], v[54:57]
	v_mfma_f32_16x16x32_bf16 v[50:53], v[158:161], v[194:197], v[50:53]
	v_mfma_f32_16x16x32_bf16 v[46:49], v[150:153], v[202:205], v[46:49]
	v_mfma_f32_16x16x32_bf16 v[42:45], v[158:161], v[202:205], v[42:45]
	v_mfma_f32_16x16x32_bf16 v[38:41], v[150:153], v[224:227], v[38:41]
	v_mfma_f32_16x16x32_bf16 v[34:37], v[158:161], v[224:227], v[34:37]
	s_setprio 0
	s_barrier
; #define PG8_STAGE(bufoff, gbase, voff) do { _Pragma("unroll") for (int _i = 0; _i < 2; ++_i) \
;         __builtin_amdgcn_global_load_lds((const unsigned*)((const char*)(gbase) + (voff)[_i]), (PG8_LAS unsigned*)(lds + (bufoff) + ldsw + _i * 8192), 16, 0, 0); } while (0)
; #define PG8_LDA(dst, b, h) do { _Pragma("unroll") for (int m = 0; m < 4; ++m) _Pragma("unroll") for (int k = 0; k < 2; ++k) dst[m][k] = *(const PG8_LAS bf16x8*)(lds + PG8_SA(b, h) + aoff + m * 2048 + k * 1024); } while (0)
; #define PG8_MMA(ai, bj, At, Bt) do { __builtin_amdgcn_s_setprio(1); _Pragma("unroll") for (int m = 0; m < 4; ++m) _Pragma("unroll") for (int n = 0; n < 2; ++n) _Pragma("unroll") for (int k = 0; k < 2; ++k) \
;         acc[ai][bj][m][n] = __builtin_amdgcn_mfma_f32_16x16x32_bf16(Bt[n][k], At[m][k], acc[ai][bj][m][n], 0, 0, 0); __builtin_amdgcn_s_setprio(0); } while (0)
; #define PG8_WAIT_V(n) asm volatile("s_waitcnt vmcnt(" #n ")" ::: "memory")
; #define PG8_WAIT_L(n) asm volatile("s_waitcnt lgkmcnt(" #n ")" ::: "memory")
; #define PG8_BAR __builtin_amdgcn_s_barrier()
; #define PG8_SCHED __builtin_amdgcn_sched_barrier(0)
; template <class Epi, class Sched>
; __device__ __forceinline__ void gemm_phase(PG8_LAS unsigned char* lds, const Gemm g, const Sched& S, const Epi& E) {
;     ...
;             PG8_LDA(At, 1, 1); PG8_STAGE(PG8_SB(1, 0), b3, voffB); PG8_STAGE(PG8_SB(1, 1), b3 + hstepB, voffB); PG8_STAGE(PG8_SA(1, 0), a3, voffA);
;             PG8_WAIT_V(8); PG8_WAIT_L(0); PG8_BAR; PG8_MMA(1, 0, At, B0); PG8_MMA(1, 1, At, B1); PG8_BAR; PG8_SCHED;
;         }
	s_add_i32 s10, s57, s87
	v_lshl_add_u64 v[168:169], v[168:169], 0, s[22:23]
	s_mov_b32 m0, s10
	ds_read_b128 v[182:185], v218 offset:49152
	ds_read_b128 v[186:189], v218 offset:50176
	ds_read_b128 v[190:193], v218 offset:51200
	ds_read_b128 v[194:197], v218 offset:52224
	ds_read_b128 v[198:201], v218 offset:53248
	ds_read_b128 v[202:205], v218 offset:54272
	ds_read_b128 v[220:223], v218 offset:55296
	ds_read_b128 v[224:227], v218 offset:56320
	global_load_lds_dwordx4 v[168:169], off
	s_add_i32 m0, s10, 0x2000
	s_add_u32 s10, s42, 0x80080
	v_lshl_add_u64 v[168:169], v[228:229], 0, s[22:23]
	s_addc_u32 s11, s43, 0
	s_add_i32 s42, s76, s87
	global_load_lds_dwordx4 v[168:169], off
	v_lshl_add_u64 v[168:169], s[10:11], 0, v[174:175]
	s_mov_b32 m0, s42
	s_nop 0
	global_load_lds_dwordx4 v[168:169], off
	v_lshl_add_u64 v[168:169], s[10:11], 0, v[170:171]
	s_add_i32 m0, s42, 0x2000
	s_nop 0
	global_load_lds_dwordx4 v[168:169], off
	v_lshl_add_u64 v[168:169], v[230:231], 0, s[22:23]
	s_mov_b32 m0, s94
	s_nop 0
	global_load_lds_dwordx4 v[168:169], off
	v_lshl_add_u64 v[168:169], v[232:233], 0, s[22:23]
	s_mov_b32 m0, s95
	s_nop 0
	global_load_lds_dwordx4 v[168:169], off
	s_waitcnt vmcnt(8)
	s_waitcnt lgkmcnt(0)
	s_barrier
	s_setprio 1
	s_waitcnt lgkmcnt(0)
	v_mfma_f32_16x16x32_bf16 v[66:69], v[74:77], v[220:223], v[66:69]
	v_mfma_f32_16x16x32_bf16 v[110:113], v[74:77], v[182:185], v[110:113]
	v_mfma_f32_16x16x32_bf16 v[106:109], v[90:93], v[182:185], v[106:109]
	v_mfma_f32_16x16x32_bf16 v[98:101], v[74:77], v[190:193], v[98:101]
	v_mfma_f32_16x16x32_bf16 v[94:97], v[90:93], v[190:193], v[94:97]
	v_mfma_f32_16x16x32_bf16 v[86:89], v[74:77], v[198:201], v[86:89]
	v_mfma_f32_16x16x32_bf16 v[82:85], v[90:93], v[198:201], v[82:85]
	v_mfma_f32_16x16x32_bf16 v[74:77], v[78:81], v[224:227], v[66:69]
	v_mfma_f32_16x16x32_bf16 v[66:69], v[90:93], v[220:223], v[70:73]
	v_mfma_f32_16x16x32_bf16 v[110:113], v[78:81], v[186:189], v[110:113]
	v_mfma_f32_16x16x32_bf16 v[106:109], v[102:105], v[186:189], v[106:109]
	v_mfma_f32_16x16x32_bf16 v[98:101], v[78:81], v[194:197], v[98:101]
	v_mfma_f32_16x16x32_bf16 v[94:97], v[102:105], v[194:197], v[94:97]
	v_mfma_f32_16x16x32_bf16 v[86:89], v[78:81], v[202:205], v[86:89]
	v_mfma_f32_16x16x32_bf16 v[82:85], v[102:105], v[202:205], v[82:85]
	v_mfma_f32_16x16x32_bf16 v[70:73], v[102:105], v[224:227], v[66:69]
	s_setprio 0
	s_setprio 1
	v_mfma_f32_16x16x32_bf16 v[30:33], v[146:149], v[182:185], v[30:33]
	v_mfma_f32_16x16x32_bf16 v[26:29], v[154:157], v[182:185], v[26:29]
	v_mfma_f32_16x16x32_bf16 v[22:25], v[146:149], v[190:193], v[22:25]
	v_mfma_f32_16x16x32_bf16 v[18:21], v[154:157], v[190:193], v[18:21]
	v_mfma_f32_16x16x32_bf16 v[14:17], v[146:149], v[198:201], v[14:17]
	v_mfma_f32_16x16x32_bf16 v[10:13], v[154:157], v[198:201], v[10:13]
	v_mfma_f32_16x16x32_bf16 v[6:9], v[146:149], v[220:223], v[6:9]
	v_mfma_f32_16x16x32_bf16 v[2:5], v[154:157], v[220:223], v[2:5]
	v_mfma_f32_16x16x32_bf16 v[30:33], v[150:153], v[186:189], v[30:33]
	v_mfma_f32_16x16x32_bf16 v[26:29], v[158:161], v[186:189], v[26:29]
	v_mfma_f32_16x16x32_bf16 v[22:25], v[150:153], v[194:197], v[22:25]
	v_mfma_f32_16x16x32_bf16 v[18:21], v[158:161], v[194:197], v[18:21]
	v_mfma_f32_16x16x32_bf16 v[14:17], v[150:153], v[202:205], v[14:17]
	v_mfma_f32_16x16x32_bf16 v[10:13], v[158:161], v[202:205], v[10:13]
	v_mfma_f32_16x16x32_bf16 v[6:9], v[150:153], v[224:227], v[6:9]
	v_mfma_f32_16x16x32_bf16 v[2:5], v[158:161], v[224:227], v[2:5]
	s_setprio 0
	s_barrier
	s_add_i32 s9, s9, 2
	s_add_u32 s28, s28, 0x100
	s_addc_u32 s29, s29, 0
	s_add_u32 s7, s7, 0x100
	s_addc_u32 s8, s8, 0
	s_cmp_gt_u32 s9, 13
	s_cbranch_scc0 .LBB0_132
	s_and_b64 vcc, exec, s[60:61]
	s_cbranch_vccz .LBB0_135
	s_barrier

; #define PG8_STAGE(bufoff, gbase, voff) do { _Pragma("unroll") for (int _i = 0; _i < 2; ++_i) \
;         __builtin_amdgcn_global_load_lds((const unsigned*)((const char*)(gbase) + (voff)[_i]), (PG8_LAS unsigned*)(lds + (bufoff) + ldsw + _i * 8192), 16, 0, 0); } while (0)
; #define PG8_LDA(dst, b, h) do { _Pragma("unroll") for (int m = 0; m < 4; ++m) _Pragma("unroll") for (int k = 0; k < 2; ++k) dst[m][k] = *(const PG8_LAS bf16x8*)(lds + PG8_SA(b, h) + aoff + m * 2048 + k * 1024); } while (0)
; #define PG8_LDB(dst, b, h) do { _Pragma("unroll") for (int n = 0; n < 2; ++n) _Pragma("unroll") for (int k = 0; k < 2; ++k) dst[n][k] = *(const PG8_LAS bf16x8*)(lds + PG8_SB(b, h) + boff + n * 2048 + k * 1024); } while (0)
; #define PG8_MMA(ai, bj, At, Bt) do { __builtin_amdgcn_s_setprio(1); _Pragma("unroll") for (int m = 0; m < 4; ++m) _Pragma("unroll") for (int n = 0; n < 2; ++n) _Pragma("unroll") for (int k = 0; k < 2; ++k) \
;         acc[ai][bj][m][n] = __builtin_amdgcn_mfma_f32_16x16x32_bf16(Bt[n][k], At[m][k], acc[ai][bj][m][n], 0, 0, 0); __builtin_amdgcn_s_setprio(0); } while (0)
; #define PG8_WAIT_V(n) asm volatile("s_waitcnt vmcnt(" #n ")" ::: "memory")
; #define PG8_WAIT_L(n) asm volatile("s_waitcnt lgkmcnt(" #n ")" ::: "memory")
; #define PG8_BAR __builtin_amdgcn_s_barrier()
; #define PG8_SCHED __builtin_amdgcn_sched_barrier(0)
; template <class Epi, class Sched>
; __device__ __forceinline__ void gemm_phase(PG8_LAS unsigned char* lds, const Gemm g, const Sched& S, const Epi& E) {
;     ...
;             PG8_LDB(B0, 0, 0); PG8_LDB(B1, 0, 1); PG8_SCHED; PG8_LDA(At, 0, 0); PG8_STAGE(PG8_SA(1, 1), a1 + hstepA, voffA);
;             PG8_WAIT_V(8); PG8_WAIT_L(0); PG8_BAR; PG8_MMA(0, 0, At, B0); PG8_MMA(0, 1, At, B1); PG8_BAR; PG8_SCHED;
;             PG8_LDA(At, 0, 1); PG8_STAGE(PG8_SB(0, 0), b2, voffB); PG8_STAGE(PG8_SB(0, 1), b2 + hstepB, voffB); PG8_STAGE(PG8_SA(0, 0), a2, voffA);
;             PG8_WAIT_V(8); PG8_WAIT_L(0); PG8_BAR; PG8_MMA(1, 0, At, B0); PG8_MMA(1, 1, At, B1); PG8_BAR; PG8_SCHED;
.LBB0_197:
	s_add_u32 s9, s28, 0xfffc0080
	s_addc_u32 s10, s29, -1
	s_add_i32 s11, 0, 0x10000
	s_cmp_eq_u32 s8, 12
	s_cselect_b32 s67, s5, s10
	s_cselect_b32 s66, s45, s9
	s_cselect_b32 s65, s43, s88
	s_cselect_b32 s64, s6, s7
	s_add_i32 s9, 0, 0x14000
	v_add_u32_e32 v142, s11, v216
	v_add_u32_e32 v168, s9, v216
	ds_read_b128 v[130:133], v142
	ds_read_b128 v[134:137], v142 offset:1024
	ds_read_b128 v[138:141], v142 offset:2048
	ds_read_b128 v[142:145], v142 offset:3072
	ds_read_b128 v[180:183], v218
	ds_read_b128 v[184:187], v218 offset:1024
	ds_read_b128 v[188:191], v218 offset:2048
	ds_read_b128 v[192:195], v218 offset:3072
	ds_read_b128 v[196:199], v218 offset:4096
	ds_read_b128 v[200:203], v218 offset:5120
	ds_read_b128 v[220:223], v218 offset:6144
	ds_read_b128 v[224:227], v218 offset:7168
	ds_read_b128 v[146:149], v168
	ds_read_b128 v[150:153], v168 offset:1024
	ds_read_b128 v[154:157], v168 offset:2048
	ds_read_b128 v[176:179], v168 offset:3072
	v_lshl_add_u64 v[168:169], s[28:29], 0, v[172:173]
	s_add_i32 m0, s61, 0xc000
	global_load_lds_dwordx4 v[168:169], off
	v_lshl_add_u64 v[168:169], s[28:29], 0, v[174:175]
	s_add_i32 m0, s61, 0xe000
	s_nop 0
	global_load_lds_dwordx4 v[168:169], off
	s_waitcnt vmcnt(8)
	s_waitcnt lgkmcnt(4)
	s_barrier
	s_setprio 1
	s_waitcnt lgkmcnt(4)
	v_mfma_f32_16x16x32_bf16 v[126:129], v[130:133], v[180:183], v[126:129]
	v_mfma_f32_16x16x32_bf16 v[122:125], v[138:141], v[180:183], v[122:125]
	v_mfma_f32_16x16x32_bf16 v[118:121], v[130:133], v[188:191], v[118:121]
	v_mfma_f32_16x16x32_bf16 v[114:117], v[138:141], v[188:191], v[114:117]
	v_mfma_f32_16x16x32_bf16 v[110:113], v[130:133], v[196:199], v[110:113]
	v_mfma_f32_16x16x32_bf16 v[106:109], v[138:141], v[196:199], v[106:109]
	v_mfma_f32_16x16x32_bf16 v[102:105], v[130:133], v[220:223], v[102:105]
	v_mfma_f32_16x16x32_bf16 v[98:101], v[138:141], v[220:223], v[98:101]
	v_mfma_f32_16x16x32_bf16 v[126:129], v[134:137], v[184:187], v[126:129]
	v_mfma_f32_16x16x32_bf16 v[122:125], v[142:145], v[184:187], v[122:125]
	v_mfma_f32_16x16x32_bf16 v[118:121], v[134:137], v[192:195], v[118:121]
	v_mfma_f32_16x16x32_bf16 v[114:117], v[142:145], v[192:195], v[114:117]
	v_mfma_f32_16x16x32_bf16 v[110:113], v[134:137], v[200:203], v[110:113]
	v_mfma_f32_16x16x32_bf16 v[106:109], v[142:145], v[200:203], v[106:109]
	v_mfma_f32_16x16x32_bf16 v[102:105], v[134:137], v[224:227], v[102:105]
	v_mfma_f32_16x16x32_bf16 v[98:101], v[142:145], v[224:227], v[98:101]
	s_setprio 0
	s_setprio 1
	s_waitcnt lgkmcnt(0)
	v_mfma_f32_16x16x32_bf16 v[62:65], v[146:149], v[180:183], v[62:65]
	v_mfma_f32_16x16x32_bf16 v[58:61], v[154:157], v[180:183], v[58:61]
	v_mfma_f32_16x16x32_bf16 v[54:57], v[146:149], v[188:191], v[54:57]
	v_mfma_f32_16x16x32_bf16 v[50:53], v[154:157], v[188:191], v[50:53]
	v_mfma_f32_16x16x32_bf16 v[46:49], v[146:149], v[196:199], v[46:49]
	v_mfma_f32_16x16x32_bf16 v[42:45], v[154:157], v[196:199], v[42:45]
	v_mfma_f32_16x16x32_bf16 v[38:41], v[146:149], v[220:223], v[38:41]
	v_mfma_f32_16x16x32_bf16 v[34:37], v[154:157], v[220:223], v[34:37]
	v_mfma_f32_16x16x32_bf16 v[62:65], v[150:153], v[184:187], v[62:65]
	v_mfma_f32_16x16x32_bf16 v[58:61], v[176:179], v[184:187], v[58:61]
	v_mfma_f32_16x16x32_bf16 v[54:57], v[150:153], v[192:195], v[54:57]
	v_mfma_f32_16x16x32_bf16 v[50:53], v[176:179], v[192:195], v[50:53]
	v_mfma_f32_16x16x32_bf16 v[46:49], v[150:153], v[200:203], v[46:49]
	v_mfma_f32_16x16x32_bf16 v[42:45], v[176:179], v[200:203], v[42:45]
	v_mfma_f32_16x16x32_bf16 v[38:41], v[150:153], v[224:227], v[38:41]
	v_mfma_f32_16x16x32_bf16 v[34:37], v[176:179], v[224:227], v[34:37]
	s_setprio 0
	s_barrier
	s_add_i32 s10, s11, s81
	v_lshl_add_u64 v[168:169], s[64:65], 0, v[0:1]
	s_mov_b32 m0, s10
	ds_read_b128 v[180:183], v218 offset:16384
	ds_read_b128 v[184:187], v218 offset:17408
	ds_read_b128 v[188:191], v218 offset:18432
	ds_read_b128 v[192:195], v218 offset:19456
	ds_read_b128 v[196:199], v218 offset:20480
	ds_read_b128 v[200:203], v218 offset:21504
	ds_read_b128 v[220:223], v218 offset:22528
	ds_read_b128 v[224:227], v218 offset:23552
	global_load_lds_dwordx4 v[168:169], off
	s_add_i32 m0, s10, 0x2000
	s_add_u32 s90, s64, 0x40000
	v_lshl_add_u64 v[204:205], s[64:65], 0, v[170:171]
	s_addc_u32 s91, s65, 0
	s_add_i32 s9, s9, s81
	global_load_lds_dwordx4 v[204:205], off
	v_lshl_add_u64 v[228:229], s[90:91], 0, v[0:1]
	s_mov_b32 m0, s9
	v_lshl_add_u64 v[230:231], s[66:67], 0, v[160:161]
	global_load_lds_dwordx4 v[228:229], off
	v_lshl_add_u64 v[228:229], s[90:91], 0, v[170:171]
	s_add_i32 m0, s9, 0x2000
	s_nop 0
	global_load_lds_dwordx4 v[228:229], off
	v_lshl_add_u64 v[228:229], s[66:67], 0, v[158:159]
	s_mov_b32 m0, s61
	s_nop 0
	global_load_lds_dwordx4 v[228:229], off
	s_mov_b32 m0, s82
	s_nop 0
	global_load_lds_dwordx4 v[230:231], off
	s_waitcnt vmcnt(8)
	s_waitcnt lgkmcnt(0)
	s_barrier
; #define PG8_STAGE(bufoff, gbase, voff) do { _Pragma("unroll") for (int _i = 0; _i < 2; ++_i) \
;         __builtin_amdgcn_global_load_lds((const unsigned*)((const char*)(gbase) + (voff)[_i]), (PG8_LAS unsigned*)(lds + (bufoff) + ldsw + _i * 8192), 16, 0, 0); } while (0)
; #define PG8_LDA(dst, b, h) do { _Pragma("unroll") for (int m = 0; m < 4; ++m) _Pragma("unroll") for (int k = 0; k < 2; ++k) dst[m][k] = *(const PG8_LAS bf16x8*)(lds + PG8_SA(b, h) + aoff + m * 2048 + k * 1024); } while (0)
; #define PG8_LDB(dst, b, h) do { _Pragma("unroll") for (int n = 0; n < 2; ++n) _Pragma("unroll") for (int k = 0; k < 2; ++k) dst[n][k] = *(const PG8_LAS bf16x8*)(lds + PG8_SB(b, h) + boff + n * 2048 + k * 1024); } while (0)
; #define PG8_MMA(ai, bj, At, Bt) do { __builtin_amdgcn_s_setprio(1); _Pragma("unroll") for (int m = 0; m < 4; ++m) _Pragma("unroll") for (int n = 0; n < 2; ++n) _Pragma("unroll") for (int k = 0; k < 2; ++k) \
;         acc[ai][bj][m][n] = __builtin_amdgcn_mfma_f32_16x16x32_bf16(Bt[n][k], At[m][k], acc[ai][bj][m][n], 0, 0, 0); __builtin_amdgcn_s_setprio(0); } while (0)
; #define PG8_WAIT_V(n) asm volatile("s_waitcnt vmcnt(" #n ")" ::: "memory")
; #define PG8_WAIT_L(n) asm volatile("s_waitcnt lgkmcnt(" #n ")" ::: "memory")
; #define PG8_BAR __builtin_amdgcn_s_barrier()
; #define PG8_SCHED __builtin_amdgcn_sched_barrier(0)
; template <class Epi, class Sched>
; __device__ __forceinline__ void gemm_phase(PG8_LAS unsigned char* lds, const Gemm g, const Sched& S, const Epi& E) {
;     ...
;             PG8_WAIT_V(8); PG8_WAIT_L(0); PG8_BAR; PG8_MMA(1, 0, At, B0); PG8_MMA(1, 1, At, B1); PG8_BAR; PG8_SCHED;
;             PG8_LDB(B0, 1, 0); PG8_LDB(B1, 1, 1); PG8_SCHED; PG8_LDA(At, 1, 0); PG8_STAGE(PG8_SA(0, 1), a2 + hstepA, voffA);
;             PG8_WAIT_V(8); PG8_WAIT_L(0); PG8_BAR; PG8_MMA(0, 0, At, B0); PG8_MMA(0, 1, At, B1); PG8_BAR; PG8_SCHED;
	s_setprio 1
	s_waitcnt lgkmcnt(0)
	v_mfma_f32_16x16x32_bf16 v[94:97], v[130:133], v[180:183], v[94:97]
	v_mfma_f32_16x16x32_bf16 v[90:93], v[138:141], v[180:183], v[90:93]
	v_mfma_f32_16x16x32_bf16 v[86:89], v[130:133], v[188:191], v[86:89]
	v_mfma_f32_16x16x32_bf16 v[82:85], v[138:141], v[188:191], v[82:85]
	v_mfma_f32_16x16x32_bf16 v[78:81], v[130:133], v[196:199], v[78:81]
	v_mfma_f32_16x16x32_bf16 v[74:77], v[138:141], v[196:199], v[74:77]
	v_mfma_f32_16x16x32_bf16 v[70:73], v[130:133], v[220:223], v[70:73]
	v_mfma_f32_16x16x32_bf16 v[66:69], v[138:141], v[220:223], v[66:69]
	v_mfma_f32_16x16x32_bf16 v[94:97], v[134:137], v[184:187], v[94:97]
	v_mfma_f32_16x16x32_bf16 v[90:93], v[142:145], v[184:187], v[90:93]
	v_mfma_f32_16x16x32_bf16 v[86:89], v[134:137], v[192:195], v[86:89]
	v_mfma_f32_16x16x32_bf16 v[82:85], v[142:145], v[192:195], v[82:85]
	v_mfma_f32_16x16x32_bf16 v[78:81], v[134:137], v[200:203], v[78:81]
	v_mfma_f32_16x16x32_bf16 v[74:77], v[142:145], v[200:203], v[74:77]
	v_mfma_f32_16x16x32_bf16 v[70:73], v[134:137], v[224:227], v[70:73]
	v_mfma_f32_16x16x32_bf16 v[66:69], v[142:145], v[224:227], v[66:69]
	s_setprio 0
	s_setprio 1
	v_mfma_f32_16x16x32_bf16 v[30:33], v[146:149], v[180:183], v[30:33]
	v_mfma_f32_16x16x32_bf16 v[26:29], v[154:157], v[180:183], v[26:29]
	v_mfma_f32_16x16x32_bf16 v[22:25], v[146:149], v[188:191], v[22:25]
	v_mfma_f32_16x16x32_bf16 v[18:21], v[154:157], v[188:191], v[18:21]
	v_mfma_f32_16x16x32_bf16 v[14:17], v[146:149], v[196:199], v[14:17]
	v_mfma_f32_16x16x32_bf16 v[10:13], v[154:157], v[196:199], v[10:13]
	v_mfma_f32_16x16x32_bf16 v[6:9], v[146:149], v[220:223], v[6:9]
	v_mfma_f32_16x16x32_bf16 v[2:5], v[154:157], v[220:223], v[2:5]
	v_mfma_f32_16x16x32_bf16 v[30:33], v[150:153], v[184:187], v[30:33]
	v_mfma_f32_16x16x32_bf16 v[26:29], v[176:179], v[184:187], v[26:29]
	v_mfma_f32_16x16x32_bf16 v[22:25], v[150:153], v[192:195], v[22:25]
	v_mfma_f32_16x16x32_bf16 v[18:21], v[176:179], v[192:195], v[18:21]
	v_mfma_f32_16x16x32_bf16 v[14:17], v[150:153], v[200:203], v[14:17]
	v_mfma_f32_16x16x32_bf16 v[10:13], v[176:179], v[200:203], v[10:13]
	v_mfma_f32_16x16x32_bf16 v[6:9], v[150:153], v[224:227], v[6:9]
	v_mfma_f32_16x16x32_bf16 v[2:5], v[176:179], v[224:227], v[2:5]
	s_setprio 0
	s_barrier
	s_add_i32 s9, 0, 0x18000
	s_add_i32 s10, 0, 0x1c000
	v_add_u32_e32 v142, s9, v216
	v_add_u32_e32 v176, s10, v216
	ds_read_b128 v[130:133], v142
	ds_read_b128 v[134:137], v142 offset:1024
	ds_read_b128 v[138:141], v142 offset:2048
	ds_read_b128 v[142:145], v142 offset:3072
	ds_read_b128 v[180:183], v218 offset:32768
	ds_read_b128 v[184:187], v218 offset:33792
	ds_read_b128 v[188:191], v218 offset:34816
	ds_read_b128 v[192:195], v218 offset:35840
	ds_read_b128 v[196:199], v218 offset:36864
	ds_read_b128 v[200:203], v218 offset:37888
	ds_read_b128 v[220:223], v218 offset:38912
	ds_read_b128 v[224:227], v218 offset:39936
	ds_read_b128 v[146:149], v176
	ds_read_b128 v[150:153], v176 offset:1024
	ds_read_b128 v[154:157], v176 offset:2048
	ds_read_b128 v[176:179], v176 offset:3072
	s_add_u32 s66, s66, 0x40000
	s_addc_u32 s67, s67, 0
	s_mov_b32 m0, s83
	v_lshl_add_u64 v[232:233], s[66:67], 0, v[158:159]
	global_load_lds_dwordx4 v[232:233], off
	v_lshl_add_u64 v[232:233], s[66:67], 0, v[160:161]
	s_mov_b32 m0, s84
	s_nop 0
	global_load_lds_dwordx4 v[232:233], off
	s_waitcnt vmcnt(8)
	s_waitcnt lgkmcnt(4)
	s_barrier
	s_setprio 1
	s_waitcnt lgkmcnt(4)
	v_mfma_f32_16x16x32_bf16 v[126:129], v[130:133], v[180:183], v[126:129]
	v_mfma_f32_16x16x32_bf16 v[122:125], v[138:141], v[180:183], v[122:125]
	v_mfma_f32_16x16x32_bf16 v[118:121], v[130:133], v[188:191], v[118:121]
	v_mfma_f32_16x16x32_bf16 v[114:117], v[138:141], v[188:191], v[114:117]
	v_mfma_f32_16x16x32_bf16 v[110:113], v[130:133], v[196:199], v[110:113]
	v_mfma_f32_16x16x32_bf16 v[106:109], v[138:141], v[196:199], v[106:109]
	v_mfma_f32_16x16x32_bf16 v[102:105], v[130:133], v[220:223], v[102:105]
	v_mfma_f32_16x16x32_bf16 v[98:101], v[138:141], v[220:223], v[98:101]
	v_mfma_f32_16x16x32_bf16 v[126:129], v[134:137], v[184:187], v[126:129]
	v_mfma_f32_16x16x32_bf16 v[122:125], v[142:145], v[184:187], v[122:125]
	v_mfma_f32_16x16x32_bf16 v[118:121], v[134:137], v[192:195], v[118:121]
	v_mfma_f32_16x16x32_bf16 v[114:117], v[142:145], v[192:195], v[114:117]
	v_mfma_f32_16x16x32_bf16 v[110:113], v[134:137], v[200:203], v[110:113]
	v_mfma_f32_16x16x32_bf16 v[106:109], v[142:145], v[200:203], v[106:109]
	v_mfma_f32_16x16x32_bf16 v[102:105], v[134:137], v[224:227], v[102:105]
	v_mfma_f32_16x16x32_bf16 v[98:101], v[142:145], v[224:227], v[98:101]
	s_setprio 0
	s_setprio 1
	s_waitcnt lgkmcnt(0)
	v_mfma_f32_16x16x32_bf16 v[62:65], v[146:149], v[180:183], v[62:65]
	v_mfma_f32_16x16x32_bf16 v[58:61], v[154:157], v[180:183], v[58:61]
	v_mfma_f32_16x16x32_bf16 v[54:57], v[146:149], v[188:191], v[54:57]
	v_mfma_f32_16x16x32_bf16 v[50:53], v[154:157], v[188:191], v[50:53]
	v_mfma_f32_16x16x32_bf16 v[46:49], v[146:149], v[196:199], v[46:49]
	v_mfma_f32_16x16x32_bf16 v[42:45], v[154:157], v[196:199], v[42:45]
	v_mfma_f32_16x16x32_bf16 v[38:41], v[146:149], v[220:223], v[38:41]
	v_mfma_f32_16x16x32_bf16 v[34:37], v[154:157], v[220:223], v[34:37]
	v_mfma_f32_16x16x32_bf16 v[62:65], v[150:153], v[184:187], v[62:65]
	v_mfma_f32_16x16x32_bf16 v[58:61], v[176:179], v[184:187], v[58:61]
	v_mfma_f32_16x16x32_bf16 v[54:57], v[150:153], v[192:195], v[54:57]
	v_mfma_f32_16x16x32_bf16 v[50:53], v[176:179], v[192:195], v[50:53]
	v_mfma_f32_16x16x32_bf16 v[46:49], v[150:153], v[200:203], v[46:49]
	v_mfma_f32_16x16x32_bf16 v[42:45], v[176:179], v[200:203], v[42:45]
	v_mfma_f32_16x16x32_bf16 v[38:41], v[150:153], v[224:227], v[38:41]
	v_mfma_f32_16x16x32_bf16 v[34:37], v[176:179], v[224:227], v[34:37]
	s_setprio 0
	s_barrier
; #define PG8_STAGE(bufoff, gbase, voff) do { _Pragma("unroll") for (int _i = 0; _i < 2; ++_i) \
;         __builtin_amdgcn_global_load_lds((const unsigned*)((const char*)(gbase) + (voff)[_i]), (PG8_LAS unsigned*)(lds + (bufoff) + ldsw + _i * 8192), 16, 0, 0); } while (0)
; #define PG8_LDA(dst, b, h) do { _Pragma("unroll") for (int m = 0; m < 4; ++m) _Pragma("unroll") for (int k = 0; k < 2; ++k) dst[m][k] = *(const PG8_LAS bf16x8*)(lds + PG8_SA(b, h) + aoff + m * 2048 + k * 1024); } while (0)
; #define PG8_MMA(ai, bj, At, Bt) do { __builtin_amdgcn_s_setprio(1); _Pragma("unroll") for (int m = 0; m < 4; ++m) _Pragma("unroll") for (int n = 0; n < 2; ++n) _Pragma("unroll") for (int k = 0; k < 2; ++k) \
;         acc[ai][bj][m][n] = __builtin_amdgcn_mfma_f32_16x16x32_bf16(Bt[n][k], At[m][k], acc[ai][bj][m][n], 0, 0, 0); __builtin_amdgcn_s_setprio(0); } while (0)
; #define PG8_WAIT_V(n) asm volatile("s_waitcnt vmcnt(" #n ")" ::: "memory")
; #define PG8_WAIT_L(n) asm volatile("s_waitcnt lgkmcnt(" #n ")" ::: "memory")
; #define PG8_BAR __builtin_amdgcn_s_barrier()
; #define PG8_SCHED __builtin_amdgcn_sched_barrier(0)
; template <class Epi, class Sched>
; __device__ __forceinline__ void gemm_phase(PG8_LAS unsigned char* lds, const Gemm g, const Sched& S, const Epi& E) {
;     ...
;             PG8_LDA(At, 1, 1); PG8_STAGE(PG8_SB(1, 0), b3, voffB); PG8_STAGE(PG8_SB(1, 1), b3 + hstepB, voffB); PG8_STAGE(PG8_SA(1, 0), a3, voffA);
;             PG8_WAIT_V(8); PG8_WAIT_L(0); PG8_BAR; PG8_MMA(1, 0, At, B0); PG8_MMA(1, 1, At, B1); PG8_BAR; PG8_SCHED;
;         }
	s_add_i32 s9, s9, s81
	v_lshl_add_u64 v[168:169], v[168:169], 0, s[22:23]
	s_mov_b32 m0, s9
	ds_read_b128 v[180:183], v218 offset:49152
	ds_read_b128 v[184:187], v218 offset:50176
	ds_read_b128 v[188:191], v218 offset:51200
	ds_read_b128 v[192:195], v218 offset:52224
	ds_read_b128 v[196:199], v218 offset:53248
	ds_read_b128 v[200:203], v218 offset:54272
	ds_read_b128 v[220:223], v218 offset:55296
	ds_read_b128 v[224:227], v218 offset:56320
	global_load_lds_dwordx4 v[168:169], off
	s_add_i32 m0, s9, 0x2000
	s_add_u32 s64, s64, 0x40080
	v_lshl_add_u64 v[168:169], v[204:205], 0, s[22:23]
	s_addc_u32 s65, s65, 0
	s_add_i32 s9, s10, s81
	global_load_lds_dwordx4 v[168:169], off
	v_lshl_add_u64 v[168:169], s[64:65], 0, v[0:1]
	s_mov_b32 m0, s9
	s_nop 0
	global_load_lds_dwordx4 v[168:169], off
	v_lshl_add_u64 v[168:169], s[64:65], 0, v[170:171]
	s_add_i32 m0, s9, 0x2000
	s_nop 0
	global_load_lds_dwordx4 v[168:169], off
	v_lshl_add_u64 v[168:169], v[228:229], 0, s[22:23]
	s_mov_b32 m0, s20
	s_nop 0
	global_load_lds_dwordx4 v[168:169], off
	v_lshl_add_u64 v[168:169], v[230:231], 0, s[22:23]
	s_mov_b32 m0, s85
	s_nop 0
	global_load_lds_dwordx4 v[168:169], off
	s_waitcnt vmcnt(8)
	s_waitcnt lgkmcnt(0)
	s_barrier
	s_setprio 1
	s_waitcnt lgkmcnt(0)
	v_mfma_f32_16x16x32_bf16 v[94:97], v[130:133], v[180:183], v[94:97]
	v_mfma_f32_16x16x32_bf16 v[90:93], v[138:141], v[180:183], v[90:93]
	v_mfma_f32_16x16x32_bf16 v[86:89], v[130:133], v[188:191], v[86:89]
	v_mfma_f32_16x16x32_bf16 v[82:85], v[138:141], v[188:191], v[82:85]
	v_mfma_f32_16x16x32_bf16 v[78:81], v[130:133], v[196:199], v[78:81]
	v_mfma_f32_16x16x32_bf16 v[74:77], v[138:141], v[196:199], v[74:77]
	v_mfma_f32_16x16x32_bf16 v[70:73], v[130:133], v[220:223], v[70:73]
	v_mfma_f32_16x16x32_bf16 v[66:69], v[138:141], v[220:223], v[66:69]
	v_mfma_f32_16x16x32_bf16 v[94:97], v[134:137], v[184:187], v[94:97]
	v_mfma_f32_16x16x32_bf16 v[90:93], v[142:145], v[184:187], v[90:93]
	v_mfma_f32_16x16x32_bf16 v[86:89], v[134:137], v[192:195], v[86:89]
	v_mfma_f32_16x16x32_bf16 v[82:85], v[142:145], v[192:195], v[82:85]
	v_mfma_f32_16x16x32_bf16 v[78:81], v[134:137], v[200:203], v[78:81]
	v_mfma_f32_16x16x32_bf16 v[74:77], v[142:145], v[200:203], v[74:77]
	v_mfma_f32_16x16x32_bf16 v[70:73], v[134:137], v[224:227], v[70:73]
	v_mfma_f32_16x16x32_bf16 v[66:69], v[142:145], v[224:227], v[66:69]
	s_setprio 0
	s_setprio 1
	v_mfma_f32_16x16x32_bf16 v[30:33], v[146:149], v[180:183], v[30:33]
	v_mfma_f32_16x16x32_bf16 v[26:29], v[154:157], v[180:183], v[26:29]
	v_mfma_f32_16x16x32_bf16 v[22:25], v[146:149], v[188:191], v[22:25]
	v_mfma_f32_16x16x32_bf16 v[18:21], v[154:157], v[188:191], v[18:21]
	v_mfma_f32_16x16x32_bf16 v[14:17], v[146:149], v[196:199], v[14:17]
	v_mfma_f32_16x16x32_bf16 v[10:13], v[154:157], v[196:199], v[10:13]
	v_mfma_f32_16x16x32_bf16 v[6:9], v[146:149], v[220:223], v[6:9]
	v_mfma_f32_16x16x32_bf16 v[2:5], v[154:157], v[220:223], v[2:5]
	v_mfma_f32_16x16x32_bf16 v[30:33], v[150:153], v[184:187], v[30:33]
	v_mfma_f32_16x16x32_bf16 v[26:29], v[176:179], v[184:187], v[26:29]
	v_mfma_f32_16x16x32_bf16 v[22:25], v[150:153], v[192:195], v[22:25]
	v_mfma_f32_16x16x32_bf16 v[18:21], v[176:179], v[192:195], v[18:21]
	v_mfma_f32_16x16x32_bf16 v[14:17], v[150:153], v[200:203], v[14:17]
	v_mfma_f32_16x16x32_bf16 v[10:13], v[176:179], v[200:203], v[10:13]
	v_mfma_f32_16x16x32_bf16 v[6:9], v[150:153], v[224:227], v[6:9]
	v_mfma_f32_16x16x32_bf16 v[2:5], v[176:179], v[224:227], v[2:5]
	s_setprio 0
	s_barrier
	s_add_i32 s8, s8, 2
	s_add_u32 s28, s28, 0x100
	s_addc_u32 s29, s29, 0
	s_add_u32 s7, s7, 0x100
	s_addc_u32 s88, s88, 0
	s_cmp_gt_u32 s8, 13
	s_cbranch_scc0 .LBB0_197
	s_and_b64 vcc, exec, s[38:39]
	s_cbranch_vccz .LBB0_200
	s_barrier

; #define PG8_STAGE(bufoff, gbase, voff) do { _Pragma("unroll") for (int _i = 0; _i < 2; ++_i) \
;         __builtin_amdgcn_global_load_lds((const unsigned*)((const char*)(gbase) + (voff)[_i]), (PG8_LAS unsigned*)(lds + (bufoff) + ldsw + _i * 8192), 16, 0, 0); } while (0)
; #define PG8_LDA(dst, b, h) do { _Pragma("unroll") for (int m = 0; m < 4; ++m) _Pragma("unroll") for (int k = 0; k < 2; ++k) dst[m][k] = *(const PG8_LAS bf16x8*)(lds + PG8_SA(b, h) + aoff + m * 2048 + k * 1024); } while (0)
; #define PG8_LDB(dst, b, h) do { _Pragma("unroll") for (int n = 0; n < 2; ++n) _Pragma("unroll") for (int k = 0; k < 2; ++k) dst[n][k] = *(const PG8_LAS bf16x8*)(lds + PG8_SB(b, h) + boff + n * 2048 + k * 1024); } while (0)
; #define PG8_MMA(ai, bj, At, Bt) do { __builtin_amdgcn_s_setprio(1); _Pragma("unroll") for (int m = 0; m < 4; ++m) _Pragma("unroll") for (int n = 0; n < 2; ++n) _Pragma("unroll") for (int k = 0; k < 2; ++k) \
;         acc[ai][bj][m][n] = __builtin_amdgcn_mfma_f32_16x16x32_bf16(Bt[n][k], At[m][k], acc[ai][bj][m][n], 0, 0, 0); __builtin_amdgcn_s_setprio(0); } while (0)
; #define PG8_WAIT_V(n) asm volatile("s_waitcnt vmcnt(" #n ")" ::: "memory")
; #define PG8_WAIT_L(n) asm volatile("s_waitcnt lgkmcnt(" #n ")" ::: "memory")
; #define PG8_BAR __builtin_amdgcn_s_barrier()
; #define PG8_SCHED __builtin_amdgcn_sched_barrier(0)
; template <class Epi, class Sched>
; __device__ __forceinline__ void gemm_phase(PG8_LAS unsigned char* lds, const Gemm g, const Sched& S, const Epi& E) {
;     ...
;             PG8_LDB(B0, 0, 0); PG8_LDB(B1, 0, 1); PG8_SCHED; PG8_LDA(At, 0, 0); PG8_STAGE(PG8_SA(1, 1), a1 + hstepA, voffA);
;             PG8_WAIT_V(8); PG8_WAIT_L(0); PG8_BAR; PG8_MMA(0, 0, At, B0); PG8_MMA(0, 1, At, B1); PG8_BAR; PG8_SCHED;
;             PG8_LDA(At, 0, 1); PG8_STAGE(PG8_SB(0, 0), b2, voffB); PG8_STAGE(PG8_SB(0, 1), b2 + hstepB, voffB); PG8_STAGE(PG8_SA(0, 0), a2, voffA);
;             PG8_WAIT_V(8); PG8_WAIT_L(0); PG8_BAR; PG8_MMA(1, 0, At, B0); PG8_MMA(1, 1, At, B1); PG8_BAR; PG8_SCHED;
.LBB0_277:
	s_add_u32 s9, s28, 0xfff80080
	s_addc_u32 s10, s29, -1
	s_add_i32 s11, 0, 0x10000
	s_cmp_eq_u32 s8, 28
	s_cselect_b32 vcc_hi, s4, s10
	s_cselect_b32 vcc_lo, s5, s9
	v_add_u32_e32 v0, s11, v182
	s_cselect_b32 s45, s13, s15
	s_cselect_b32 s44, s6, s7
	s_add_i32 s9, 0, 0x14000
	ds_read_b128 v[130:133], v0
	ds_read_b128 v[148:151], v0 offset:1024
	ds_read_b128 v[152:155], v0 offset:2048
	ds_read_b128 v[156:159], v0 offset:3072
	ds_read_b128 v[216:219], v200
	ds_read_b128 v[220:223], v200 offset:1024
	ds_read_b128 v[224:227], v200 offset:2048
	ds_read_b128 v[228:231], v200 offset:3072
	ds_read_b128 v[232:235], v200 offset:4096
	ds_read_b128 v[236:239], v200 offset:5120
	ds_read_b128 v[240:243], v200 offset:6144
	ds_read_b128 v[244:247], v200 offset:7168
	v_add_u32_e32 v0, s9, v182
	ds_read_b128 v[170:173], v0
	ds_read_b128 v[174:177], v0 offset:1024
	ds_read_b128 v[178:181], v0 offset:2048
	ds_read_b128 v[202:205], v0 offset:3072
	v_lshl_add_u64 v[160:161], s[28:29], 0, v[144:145]
	s_add_i32 m0, s39, 0xc000
	global_load_lds_dwordx4 v[160:161], off
	v_lshl_add_u64 v[160:161], s[28:29], 0, v[146:147]
	s_add_i32 m0, s39, 0xe000
	s_nop 0
	global_load_lds_dwordx4 v[160:161], off
	s_waitcnt vmcnt(8)
	s_waitcnt lgkmcnt(4)
	s_barrier
	s_setprio 1
	s_waitcnt lgkmcnt(4)
	v_mfma_f32_16x16x32_bf16 v[126:129], v[130:133], v[216:219], v[126:129]
	v_mfma_f32_16x16x32_bf16 v[122:125], v[152:155], v[216:219], v[122:125]
	v_mfma_f32_16x16x32_bf16 v[110:113], v[130:133], v[224:227], v[110:113]
	v_mfma_f32_16x16x32_bf16 v[106:109], v[152:155], v[224:227], v[106:109]
	v_mfma_f32_16x16x32_bf16 v[94:97], v[130:133], v[232:235], v[94:97]
	v_mfma_f32_16x16x32_bf16 v[90:93], v[152:155], v[232:235], v[90:93]
	v_mfma_f32_16x16x32_bf16 v[78:81], v[130:133], v[240:243], v[78:81]
	v_mfma_f32_16x16x32_bf16 v[74:77], v[152:155], v[240:243], v[74:77]
	v_mfma_f32_16x16x32_bf16 v[126:129], v[148:151], v[220:223], v[126:129]
	v_mfma_f32_16x16x32_bf16 v[122:125], v[156:159], v[220:223], v[122:125]
	v_mfma_f32_16x16x32_bf16 v[110:113], v[148:151], v[228:231], v[110:113]
	v_mfma_f32_16x16x32_bf16 v[106:109], v[156:159], v[228:231], v[106:109]
	v_mfma_f32_16x16x32_bf16 v[94:97], v[148:151], v[236:239], v[94:97]
	v_mfma_f32_16x16x32_bf16 v[90:93], v[156:159], v[236:239], v[90:93]
	v_mfma_f32_16x16x32_bf16 v[78:81], v[148:151], v[244:247], v[78:81]
	v_mfma_f32_16x16x32_bf16 v[74:77], v[156:159], v[244:247], v[74:77]
	s_setprio 0
	s_setprio 1
	s_waitcnt lgkmcnt(0)
	v_mfma_f32_16x16x32_bf16 v[118:121], v[170:173], v[216:219], v[118:121]
	v_mfma_f32_16x16x32_bf16 v[114:117], v[178:181], v[216:219], v[114:117]
	v_mfma_f32_16x16x32_bf16 v[102:105], v[170:173], v[224:227], v[102:105]
	v_mfma_f32_16x16x32_bf16 v[98:101], v[178:181], v[224:227], v[98:101]
	v_mfma_f32_16x16x32_bf16 v[86:89], v[170:173], v[232:235], v[86:89]
	v_mfma_f32_16x16x32_bf16 v[82:85], v[178:181], v[232:235], v[82:85]
	v_mfma_f32_16x16x32_bf16 v[70:73], v[170:173], v[240:243], v[70:73]
	v_mfma_f32_16x16x32_bf16 v[66:69], v[178:181], v[240:243], v[66:69]
	v_mfma_f32_16x16x32_bf16 v[118:121], v[174:177], v[220:223], v[118:121]
	v_mfma_f32_16x16x32_bf16 v[114:117], v[202:205], v[220:223], v[114:117]
	v_mfma_f32_16x16x32_bf16 v[102:105], v[174:177], v[228:231], v[102:105]
	v_mfma_f32_16x16x32_bf16 v[98:101], v[202:205], v[228:231], v[98:101]
	v_mfma_f32_16x16x32_bf16 v[86:89], v[174:177], v[236:239], v[86:89]
	v_mfma_f32_16x16x32_bf16 v[82:85], v[202:205], v[236:239], v[82:85]
	v_mfma_f32_16x16x32_bf16 v[70:73], v[174:177], v[244:247], v[70:73]
	v_mfma_f32_16x16x32_bf16 v[66:69], v[202:205], v[244:247], v[66:69]
	s_setprio 0
	s_barrier
	s_add_i32 s10, s11, s20
	v_lshl_add_u64 v[160:161], s[44:45], 0, v[136:137]
	s_mov_b32 m0, s10
	ds_read_b128 v[216:219], v200 offset:16384
	ds_read_b128 v[220:223], v200 offset:17408
	ds_read_b128 v[224:227], v200 offset:18432
	ds_read_b128 v[228:231], v200 offset:19456
	ds_read_b128 v[232:235], v200 offset:20480
	ds_read_b128 v[236:239], v200 offset:21504
	ds_read_b128 v[240:243], v200 offset:22528
	ds_read_b128 v[244:247], v200 offset:23552
	global_load_lds_dwordx4 v[160:161], off
	s_add_i32 m0, s10, 0x2000
	s_add_u32 s90, s44, 0x80000
	v_lshl_add_u64 v[248:249], s[44:45], 0, v[140:141]
	s_addc_u32 s91, s45, 0
	s_add_i32 s9, s9, s20
	global_load_lds_dwordx4 v[248:249], off
	v_lshl_add_u64 v[250:251], s[90:91], 0, v[136:137]
	s_mov_b32 m0, s9
	v_lshl_add_u64 v[252:253], vcc, 0, v[138:139]
	global_load_lds_dwordx4 v[250:251], off
	v_lshl_add_u64 v[250:251], s[90:91], 0, v[140:141]
	s_add_i32 m0, s9, 0x2000
	s_nop 0
	global_load_lds_dwordx4 v[250:251], off
	v_lshl_add_u64 v[250:251], vcc, 0, v[134:135]
	s_mov_b32 m0, s39
	s_nop 0
	global_load_lds_dwordx4 v[250:251], off
	s_mov_b32 m0, s69
	s_nop 0
	global_load_lds_dwordx4 v[252:253], off
	s_waitcnt vmcnt(8)
	s_waitcnt lgkmcnt(0)
	s_barrier
; #define PG8_STAGE(bufoff, gbase, voff) do { _Pragma("unroll") for (int _i = 0; _i < 2; ++_i) \
;         __builtin_amdgcn_global_load_lds((const unsigned*)((const char*)(gbase) + (voff)[_i]), (PG8_LAS unsigned*)(lds + (bufoff) + ldsw + _i * 8192), 16, 0, 0); } while (0)
; #define PG8_LDA(dst, b, h) do { _Pragma("unroll") for (int m = 0; m < 4; ++m) _Pragma("unroll") for (int k = 0; k < 2; ++k) dst[m][k] = *(const PG8_LAS bf16x8*)(lds + PG8_SA(b, h) + aoff + m * 2048 + k * 1024); } while (0)
; #define PG8_LDB(dst, b, h) do { _Pragma("unroll") for (int n = 0; n < 2; ++n) _Pragma("unroll") for (int k = 0; k < 2; ++k) dst[n][k] = *(const PG8_LAS bf16x8*)(lds + PG8_SB(b, h) + boff + n * 2048 + k * 1024); } while (0)
; #define PG8_MMA(ai, bj, At, Bt) do { __builtin_amdgcn_s_setprio(1); _Pragma("unroll") for (int m = 0; m < 4; ++m) _Pragma("unroll") for (int n = 0; n < 2; ++n) _Pragma("unroll") for (int k = 0; k < 2; ++k) \
;         acc[ai][bj][m][n] = __builtin_amdgcn_mfma_f32_16x16x32_bf16(Bt[n][k], At[m][k], acc[ai][bj][m][n], 0, 0, 0); __builtin_amdgcn_s_setprio(0); } while (0)
; #define PG8_WAIT_V(n) asm volatile("s_waitcnt vmcnt(" #n ")" ::: "memory")
; #define PG8_WAIT_L(n) asm volatile("s_waitcnt lgkmcnt(" #n ")" ::: "memory")
; #define PG8_BAR __builtin_amdgcn_s_barrier()
; #define PG8_SCHED __builtin_amdgcn_sched_barrier(0)
; template <class Epi, class Sched>
; __device__ __forceinline__ void gemm_phase(PG8_LAS unsigned char* lds, const Gemm g, const Sched& S, const Epi& E) {
;     ...
;             PG8_WAIT_V(8); PG8_WAIT_L(0); PG8_BAR; PG8_MMA(1, 0, At, B0); PG8_MMA(1, 1, At, B1); PG8_BAR; PG8_SCHED;
;             PG8_LDB(B0, 1, 0); PG8_LDB(B1, 1, 1); PG8_SCHED; PG8_LDA(At, 1, 0); PG8_STAGE(PG8_SA(0, 1), a2 + hstepA, voffA);
;             PG8_WAIT_V(8); PG8_WAIT_L(0); PG8_BAR; PG8_MMA(0, 0, At, B0); PG8_MMA(0, 1, At, B1); PG8_BAR; PG8_SCHED;
	s_setprio 1
	s_waitcnt lgkmcnt(0)
	v_mfma_f32_16x16x32_bf16 v[62:65], v[130:133], v[216:219], v[62:65]
	v_mfma_f32_16x16x32_bf16 v[58:61], v[152:155], v[216:219], v[58:61]
	v_mfma_f32_16x16x32_bf16 v[46:49], v[130:133], v[224:227], v[46:49]
	v_mfma_f32_16x16x32_bf16 v[42:45], v[152:155], v[224:227], v[42:45]
	v_mfma_f32_16x16x32_bf16 v[30:33], v[130:133], v[232:235], v[30:33]
	v_mfma_f32_16x16x32_bf16 v[26:29], v[152:155], v[232:235], v[26:29]
	v_mfma_f32_16x16x32_bf16 v[14:17], v[130:133], v[240:243], v[14:17]
	v_mfma_f32_16x16x32_bf16 v[10:13], v[152:155], v[240:243], v[10:13]
	v_mfma_f32_16x16x32_bf16 v[62:65], v[148:151], v[220:223], v[62:65]
	v_mfma_f32_16x16x32_bf16 v[58:61], v[156:159], v[220:223], v[58:61]
	v_mfma_f32_16x16x32_bf16 v[46:49], v[148:151], v[228:231], v[46:49]
	v_mfma_f32_16x16x32_bf16 v[42:45], v[156:159], v[228:231], v[42:45]
	v_mfma_f32_16x16x32_bf16 v[30:33], v[148:151], v[236:239], v[30:33]
	v_mfma_f32_16x16x32_bf16 v[26:29], v[156:159], v[236:239], v[26:29]
	v_mfma_f32_16x16x32_bf16 v[14:17], v[148:151], v[244:247], v[14:17]
	v_mfma_f32_16x16x32_bf16 v[10:13], v[156:159], v[244:247], v[10:13]
	s_setprio 0
	s_setprio 1
	v_mfma_f32_16x16x32_bf16 v[54:57], v[170:173], v[216:219], v[54:57]
	v_mfma_f32_16x16x32_bf16 v[50:53], v[178:181], v[216:219], v[50:53]
	v_mfma_f32_16x16x32_bf16 v[38:41], v[170:173], v[224:227], v[38:41]
	v_mfma_f32_16x16x32_bf16 v[34:37], v[178:181], v[224:227], v[34:37]
	v_mfma_f32_16x16x32_bf16 v[22:25], v[170:173], v[232:235], v[22:25]
	v_mfma_f32_16x16x32_bf16 v[18:21], v[178:181], v[232:235], v[18:21]
	v_mfma_f32_16x16x32_bf16 v[6:9], v[170:173], v[240:243], v[6:9]
	v_mfma_f32_16x16x32_bf16 v[2:5], v[178:181], v[240:243], v[2:5]
	v_mfma_f32_16x16x32_bf16 v[54:57], v[174:177], v[220:223], v[54:57]
	v_mfma_f32_16x16x32_bf16 v[50:53], v[202:205], v[220:223], v[50:53]
	v_mfma_f32_16x16x32_bf16 v[38:41], v[174:177], v[228:231], v[38:41]
	v_mfma_f32_16x16x32_bf16 v[34:37], v[202:205], v[228:231], v[34:37]
	v_mfma_f32_16x16x32_bf16 v[22:25], v[174:177], v[236:239], v[22:25]
	v_mfma_f32_16x16x32_bf16 v[18:21], v[202:205], v[236:239], v[18:21]
	v_mfma_f32_16x16x32_bf16 v[6:9], v[174:177], v[244:247], v[6:9]
	v_mfma_f32_16x16x32_bf16 v[2:5], v[202:205], v[244:247], v[2:5]
	s_setprio 0
	s_barrier
	s_add_i32 s9, 0, 0x18000
	v_add_u32_e32 v0, s9, v182
	s_add_i32 s10, 0, 0x1c000
	ds_read_b128 v[130:133], v0
	ds_read_b128 v[148:151], v0 offset:1024
	ds_read_b128 v[152:155], v0 offset:2048
	ds_read_b128 v[156:159], v0 offset:3072
	ds_read_b128 v[216:219], v200 offset:32768
	ds_read_b128 v[220:223], v200 offset:33792
	ds_read_b128 v[224:227], v200 offset:34816
	ds_read_b128 v[228:231], v200 offset:35840
	ds_read_b128 v[232:235], v200 offset:36864
	ds_read_b128 v[236:239], v200 offset:37888
	ds_read_b128 v[240:243], v200 offset:38912
	ds_read_b128 v[244:247], v200 offset:39936
	v_add_u32_e32 v0, s10, v182
	ds_read_b128 v[170:173], v0
	ds_read_b128 v[174:177], v0 offset:1024
	ds_read_b128 v[178:181], v0 offset:2048
	ds_read_b128 v[202:205], v0 offset:3072
	s_add_u32 s90, vcc_lo, 0x80000
	s_addc_u32 s91, vcc_hi, 0
	s_mov_b32 m0, s80
	v_lshl_add_u64 v[168:169], s[90:91], 0, v[134:135]
	global_load_lds_dwordx4 v[168:169], off
	v_lshl_add_u64 v[168:169], s[90:91], 0, v[138:139]
	s_mov_b32 m0, s81
	s_nop 0
	global_load_lds_dwordx4 v[168:169], off
	s_waitcnt vmcnt(8)
	s_waitcnt lgkmcnt(4)
	s_barrier
	s_setprio 1
	s_waitcnt lgkmcnt(4)
	v_mfma_f32_16x16x32_bf16 v[126:129], v[130:133], v[216:219], v[126:129]
	v_mfma_f32_16x16x32_bf16 v[122:125], v[152:155], v[216:219], v[122:125]
	v_mfma_f32_16x16x32_bf16 v[110:113], v[130:133], v[224:227], v[110:113]
	v_mfma_f32_16x16x32_bf16 v[106:109], v[152:155], v[224:227], v[106:109]
	v_mfma_f32_16x16x32_bf16 v[94:97], v[130:133], v[232:235], v[94:97]
	v_mfma_f32_16x16x32_bf16 v[90:93], v[152:155], v[232:235], v[90:93]
	v_mfma_f32_16x16x32_bf16 v[78:81], v[130:133], v[240:243], v[78:81]
	v_mfma_f32_16x16x32_bf16 v[74:77], v[152:155], v[240:243], v[74:77]
	v_mfma_f32_16x16x32_bf16 v[126:129], v[148:151], v[220:223], v[126:129]
	v_mfma_f32_16x16x32_bf16 v[122:125], v[156:159], v[220:223], v[122:125]
	v_mfma_f32_16x16x32_bf16 v[110:113], v[148:151], v[228:231], v[110:113]
	v_mfma_f32_16x16x32_bf16 v[106:109], v[156:159], v[228:231], v[106:109]
	v_mfma_f32_16x16x32_bf16 v[94:97], v[148:151], v[236:239], v[94:97]
	v_mfma_f32_16x16x32_bf16 v[90:93], v[156:159], v[236:239], v[90:93]
	v_mfma_f32_16x16x32_bf16 v[78:81], v[148:151], v[244:247], v[78:81]
	v_mfma_f32_16x16x32_bf16 v[74:77], v[156:159], v[244:247], v[74:77]
	s_setprio 0
	s_setprio 1
	s_waitcnt lgkmcnt(0)
	v_mfma_f32_16x16x32_bf16 v[118:121], v[170:173], v[216:219], v[118:121]
	v_mfma_f32_16x16x32_bf16 v[114:117], v[178:181], v[216:219], v[114:117]
	v_mfma_f32_16x16x32_bf16 v[102:105], v[170:173], v[224:227], v[102:105]
	v_mfma_f32_16x16x32_bf16 v[98:101], v[178:181], v[224:227], v[98:101]
	v_mfma_f32_16x16x32_bf16 v[86:89], v[170:173], v[232:235], v[86:89]
	v_mfma_f32_16x16x32_bf16 v[82:85], v[178:181], v[232:235], v[82:85]
	v_mfma_f32_16x16x32_bf16 v[70:73], v[170:173], v[240:243], v[70:73]
	v_mfma_f32_16x16x32_bf16 v[66:69], v[178:181], v[240:243], v[66:69]
	v_mfma_f32_16x16x32_bf16 v[118:121], v[174:177], v[220:223], v[118:121]
	v_mfma_f32_16x16x32_bf16 v[114:117], v[202:205], v[220:223], v[114:117]
	v_mfma_f32_16x16x32_bf16 v[102:105], v[174:177], v[228:231], v[102:105]
	v_mfma_f32_16x16x32_bf16 v[98:101], v[202:205], v[228:231], v[98:101]
	v_mfma_f32_16x16x32_bf16 v[86:89], v[174:177], v[236:239], v[86:89]
	v_mfma_f32_16x16x32_bf16 v[82:85], v[202:205], v[236:239], v[82:85]
	v_mfma_f32_16x16x32_bf16 v[70:73], v[174:177], v[244:247], v[70:73]
	v_mfma_f32_16x16x32_bf16 v[66:69], v[202:205], v[244:247], v[66:69]
	s_setprio 0
	s_barrier
; #define PG8_STAGE(bufoff, gbase, voff) do { _Pragma("unroll") for (int _i = 0; _i < 2; ++_i) \
;         __builtin_amdgcn_global_load_lds((const unsigned*)((const char*)(gbase) + (voff)[_i]), (PG8_LAS unsigned*)(lds + (bufoff) + ldsw + _i * 8192), 16, 0, 0); } while (0)
; #define PG8_LDA(dst, b, h) do { _Pragma("unroll") for (int m = 0; m < 4; ++m) _Pragma("unroll") for (int k = 0; k < 2; ++k) dst[m][k] = *(const PG8_LAS bf16x8*)(lds + PG8_SA(b, h) + aoff + m * 2048 + k * 1024); } while (0)
; #define PG8_MMA(ai, bj, At, Bt) do { __builtin_amdgcn_s_setprio(1); _Pragma("unroll") for (int m = 0; m < 4; ++m) _Pragma("unroll") for (int n = 0; n < 2; ++n) _Pragma("unroll") for (int k = 0; k < 2; ++k) \
;         acc[ai][bj][m][n] = __builtin_amdgcn_mfma_f32_16x16x32_bf16(Bt[n][k], At[m][k], acc[ai][bj][m][n], 0, 0, 0); __builtin_amdgcn_s_setprio(0); } while (0)
; #define PG8_WAIT_V(n) asm volatile("s_waitcnt vmcnt(" #n ")" ::: "memory")
; #define PG8_WAIT_L(n) asm volatile("s_waitcnt lgkmcnt(" #n ")" ::: "memory")
; #define PG8_BAR __builtin_amdgcn_s_barrier()
; #define PG8_SCHED __builtin_amdgcn_sched_barrier(0)
; template <class Epi, class Sched>
; __device__ __forceinline__ void gemm_phase(PG8_LAS unsigned char* lds, const Gemm g, const Sched& S, const Epi& E) {
;     ...
;             PG8_LDA(At, 1, 1); PG8_STAGE(PG8_SB(1, 0), b3, voffB); PG8_STAGE(PG8_SB(1, 1), b3 + hstepB, voffB); PG8_STAGE(PG8_SA(1, 0), a3, voffA);
;             PG8_WAIT_V(8); PG8_WAIT_L(0); PG8_BAR; PG8_MMA(1, 0, At, B0); PG8_MMA(1, 1, At, B1); PG8_BAR; PG8_SCHED;
;         }
	s_add_i32 s9, s9, s20
	v_lshl_add_u64 v[160:161], v[160:161], 0, s[22:23]
	s_mov_b32 m0, s9
	ds_read_b128 v[216:219], v200 offset:49152
	ds_read_b128 v[220:223], v200 offset:50176
	ds_read_b128 v[224:227], v200 offset:51200
	ds_read_b128 v[228:231], v200 offset:52224
	ds_read_b128 v[232:235], v200 offset:53248
	ds_read_b128 v[236:239], v200 offset:54272
	ds_read_b128 v[240:243], v200 offset:55296
	ds_read_b128 v[244:247], v200 offset:56320
	global_load_lds_dwordx4 v[160:161], off
	s_add_i32 m0, s9, 0x2000
	s_add_u32 s44, s44, 0x80080
	v_lshl_add_u64 v[160:161], v[248:249], 0, s[22:23]
	s_addc_u32 s45, s45, 0
	s_add_i32 s9, s10, s20
	global_load_lds_dwordx4 v[160:161], off
	v_lshl_add_u64 v[160:161], s[44:45], 0, v[136:137]
	s_mov_b32 m0, s9
	s_nop 0
	global_load_lds_dwordx4 v[160:161], off
	v_lshl_add_u64 v[160:161], s[44:45], 0, v[140:141]
	s_add_i32 m0, s9, 0x2000
	s_nop 0
	global_load_lds_dwordx4 v[160:161], off
	v_lshl_add_u64 v[160:161], v[250:251], 0, s[22:23]
	s_mov_b32 m0, s82
	s_nop 0
	global_load_lds_dwordx4 v[160:161], off
	v_lshl_add_u64 v[160:161], v[252:253], 0, s[22:23]
	s_mov_b32 m0, s83
	s_nop 0
	global_load_lds_dwordx4 v[160:161], off
	s_waitcnt vmcnt(8)
	s_waitcnt lgkmcnt(0)
	s_barrier
	s_setprio 1
	s_waitcnt lgkmcnt(0)
	v_mfma_f32_16x16x32_bf16 v[62:65], v[130:133], v[216:219], v[62:65]
	v_mfma_f32_16x16x32_bf16 v[58:61], v[152:155], v[216:219], v[58:61]
	v_mfma_f32_16x16x32_bf16 v[46:49], v[130:133], v[224:227], v[46:49]
	v_mfma_f32_16x16x32_bf16 v[42:45], v[152:155], v[224:227], v[42:45]
	v_mfma_f32_16x16x32_bf16 v[30:33], v[130:133], v[232:235], v[30:33]
	v_mfma_f32_16x16x32_bf16 v[26:29], v[152:155], v[232:235], v[26:29]
	v_mfma_f32_16x16x32_bf16 v[14:17], v[130:133], v[240:243], v[14:17]
	v_mfma_f32_16x16x32_bf16 v[10:13], v[152:155], v[240:243], v[10:13]
	v_mfma_f32_16x16x32_bf16 v[62:65], v[148:151], v[220:223], v[62:65]
	v_mfma_f32_16x16x32_bf16 v[58:61], v[156:159], v[220:223], v[58:61]
	v_mfma_f32_16x16x32_bf16 v[46:49], v[148:151], v[228:231], v[46:49]
	v_mfma_f32_16x16x32_bf16 v[42:45], v[156:159], v[228:231], v[42:45]
	v_mfma_f32_16x16x32_bf16 v[30:33], v[148:151], v[236:239], v[30:33]
	v_mfma_f32_16x16x32_bf16 v[26:29], v[156:159], v[236:239], v[26:29]
	v_mfma_f32_16x16x32_bf16 v[14:17], v[148:151], v[244:247], v[14:17]
	v_mfma_f32_16x16x32_bf16 v[10:13], v[156:159], v[244:247], v[10:13]
	s_setprio 0
	s_setprio 1
	v_mfma_f32_16x16x32_bf16 v[54:57], v[170:173], v[216:219], v[54:57]
	v_mfma_f32_16x16x32_bf16 v[50:53], v[178:181], v[216:219], v[50:53]
	v_mfma_f32_16x16x32_bf16 v[38:41], v[170:173], v[224:227], v[38:41]
	v_mfma_f32_16x16x32_bf16 v[34:37], v[178:181], v[224:227], v[34:37]
	v_mfma_f32_16x16x32_bf16 v[22:25], v[170:173], v[232:235], v[22:25]
	v_mfma_f32_16x16x32_bf16 v[18:21], v[178:181], v[232:235], v[18:21]
	v_mfma_f32_16x16x32_bf16 v[6:9], v[170:173], v[240:243], v[6:9]
	v_mfma_f32_16x16x32_bf16 v[2:5], v[178:181], v[240:243], v[2:5]
	v_mfma_f32_16x16x32_bf16 v[54:57], v[174:177], v[220:223], v[54:57]
	v_mfma_f32_16x16x32_bf16 v[50:53], v[202:205], v[220:223], v[50:53]
	v_mfma_f32_16x16x32_bf16 v[38:41], v[174:177], v[228:231], v[38:41]
	v_mfma_f32_16x16x32_bf16 v[34:37], v[202:205], v[228:231], v[34:37]
	v_mfma_f32_16x16x32_bf16 v[22:25], v[174:177], v[236:239], v[22:25]
	v_mfma_f32_16x16x32_bf16 v[18:21], v[202:205], v[236:239], v[18:21]
	v_mfma_f32_16x16x32_bf16 v[6:9], v[174:177], v[244:247], v[6:9]
	v_mfma_f32_16x16x32_bf16 v[2:5], v[202:205], v[244:247], v[2:5]
	s_setprio 0
	s_barrier
	s_add_i32 s8, s8, 2
	s_add_u32 s28, s28, 0x100
	s_addc_u32 s29, s29, 0
	s_add_u32 s7, s7, 0x100
	s_addc_u32 s15, s15, 0
	s_cmp_gt_u32 s8, 29
	s_cbranch_scc0 .LBB0_277
	s_and_b64 vcc, exec, s[60:61]
	s_cbranch_vccz .LBB0_280
	s_barrier
